# P0 mod GEMV: the four 16-row weight batches of a 64-row block unrolled and double-buffered (next batch's 16 loads in flight during the current batch's FMAs, counted vmcnt); stacked on attention fast p
# speedup vs baseline: 1.0029x; 1.0002x over previous
.LBB0_16:
	v_add_co_u32_e32 v2, vcc, 0xffde4000, v100
	s_nop 1
	v_addc_co_u32_e32 v3, vcc, -1, v101, vcc
	v_add_co_u32_e32 v4, vcc, 0xffe08000, v100
	s_nop 1
	v_addc_co_u32_e32 v5, vcc, -1, v101, vcc
	global_load_dwordx4 v[112:115], v[2:3], off nt
	global_load_dwordx4 v[116:119], v[4:5], off nt
	v_add_co_u32_e32 v2, vcc, 0xffe2c000, v100
	s_nop 1
	v_addc_co_u32_e32 v3, vcc, -1, v101, vcc
	v_add_co_u32_e32 v4, vcc, 0xffe50000, v100
	s_nop 1
	v_addc_co_u32_e32 v5, vcc, -1, v101, vcc
	global_load_dwordx4 v[90:93], v[2:3], off nt
	global_load_dwordx4 v[86:89], v[4:5], off nt
	v_add_co_u32_e32 v2, vcc, 0xffe74000, v100
	s_nop 1
	v_addc_co_u32_e32 v3, vcc, -1, v101, vcc
	v_add_co_u32_e32 v4, vcc, 0xffe98000, v100
	s_nop 1
	v_addc_co_u32_e32 v5, vcc, -1, v101, vcc
	global_load_dwordx4 v[82:85], v[2:3], off nt
	global_load_dwordx4 v[78:81], v[4:5], off nt
	v_add_co_u32_e32 v2, vcc, 0xffebc000, v100
	s_nop 1
	v_addc_co_u32_e32 v3, vcc, -1, v101, vcc
	v_add_co_u32_e32 v4, vcc, 0xffee0000, v100
	s_nop 1
	v_addc_co_u32_e32 v5, vcc, -1, v101, vcc
	global_load_dwordx4 v[74:77], v[2:3], off nt
	global_load_dwordx4 v[70:73], v[4:5], off nt
	v_add_co_u32_e32 v2, vcc, 0xfff04000, v100
	s_nop 1
	v_addc_co_u32_e32 v3, vcc, -1, v101, vcc
	v_add_co_u32_e32 v4, vcc, 0xfff28000, v100
	s_nop 1
	v_addc_co_u32_e32 v5, vcc, -1, v101, vcc
	global_load_dwordx4 v[66:69], v[2:3], off nt
	global_load_dwordx4 v[62:65], v[4:5], off nt
	v_add_co_u32_e32 v2, vcc, 0xfff4c000, v100
	s_nop 1
	v_addc_co_u32_e32 v3, vcc, -1, v101, vcc
	v_add_co_u32_e32 v4, vcc, 0xfff70000, v100
	s_nop 1
	v_addc_co_u32_e32 v5, vcc, -1, v101, vcc
	global_load_dwordx4 v[46:49], v[2:3], off nt
	global_load_dwordx4 v[18:21], v[4:5], off nt
	v_add_co_u32_e32 v2, vcc, 0xfff94000, v100
	s_nop 1
	v_addc_co_u32_e32 v3, vcc, -1, v101, vcc
	v_add_co_u32_e32 v4, vcc, 0xfffb8000, v100
	s_nop 1
	v_addc_co_u32_e32 v5, vcc, -1, v101, vcc
	global_load_dwordx4 v[14:17], v[2:3], off nt
	global_load_dwordx4 v[10:13], v[4:5], off nt
	v_add_co_u32_e32 v2, vcc, 0xfffdc000, v100
	s_nop 1
	v_addc_co_u32_e32 v3, vcc, -1, v101, vcc
	global_load_dwordx4 v[6:9], v[2:3], off nt
	s_nop 0
	global_load_dwordx4 v[2:5], v[100:101], off nt
	s_mov_b64 s[8:9], 0x240000
	v_lshl_add_u64 v[100:101], v[100:101], 0, s[8:9]
	v_add_co_u32_e32 v180, vcc, 0xffde4000, v100
	s_nop 1
	v_addc_co_u32_e32 v181, vcc, -1, v101, vcc
	v_add_co_u32_e32 v182, vcc, 0xffe08000, v100
	s_nop 1
	v_addc_co_u32_e32 v183, vcc, -1, v101, vcc
	global_load_dwordx4 v[120:123], v[180:181], off nt
	global_load_dwordx4 v[124:127], v[182:183], off nt
	v_add_co_u32_e32 v180, vcc, 0xffe2c000, v100
	s_nop 1
	v_addc_co_u32_e32 v181, vcc, -1, v101, vcc
	v_add_co_u32_e32 v182, vcc, 0xffe50000, v100
	s_nop 1
	v_addc_co_u32_e32 v183, vcc, -1, v101, vcc
	global_load_dwordx4 v[128:131], v[180:181], off nt
	global_load_dwordx4 v[132:135], v[182:183], off nt
	v_add_co_u32_e32 v180, vcc, 0xffe74000, v100
	s_nop 1
	v_addc_co_u32_e32 v181, vcc, -1, v101, vcc
	v_add_co_u32_e32 v182, vcc, 0xffe98000, v100
	s_nop 1
	v_addc_co_u32_e32 v183, vcc, -1, v101, vcc
	global_load_dwordx4 v[136:139], v[180:181], off nt
	global_load_dwordx4 v[140:143], v[182:183], off nt
	v_add_co_u32_e32 v180, vcc, 0xffebc000, v100
	s_nop 1
	v_addc_co_u32_e32 v181, vcc, -1, v101, vcc
	v_add_co_u32_e32 v182, vcc, 0xffee0000, v100
	s_nop 1
	v_addc_co_u32_e32 v183, vcc, -1, v101, vcc
	global_load_dwordx4 v[144:147], v[180:181], off nt
	global_load_dwordx4 v[148:151], v[182:183], off nt
	v_add_co_u32_e32 v180, vcc, 0xfff04000, v100
	s_nop 1
	v_addc_co_u32_e32 v181, vcc, -1, v101, vcc
	v_add_co_u32_e32 v182, vcc, 0xfff28000, v100
	s_nop 1
	v_addc_co_u32_e32 v183, vcc, -1, v101, vcc
	global_load_dwordx4 v[152:155], v[180:181], off nt
	global_load_dwordx4 v[156:159], v[182:183], off nt
	v_add_co_u32_e32 v180, vcc, 0xfff4c000, v100
	s_nop 1
	v_addc_co_u32_e32 v181, vcc, -1, v101, vcc
	v_add_co_u32_e32 v182, vcc, 0xfff70000, v100
	s_nop 1
	v_addc_co_u32_e32 v183, vcc, -1, v101, vcc
	global_load_dwordx4 v[160:163], v[180:181], off nt
	global_load_dwordx4 v[164:167], v[182:183], off nt
	v_add_co_u32_e32 v180, vcc, 0xfff94000, v100
	s_nop 1
	v_addc_co_u32_e32 v181, vcc, -1, v101, vcc
	v_add_co_u32_e32 v182, vcc, 0xfffb8000, v100
	s_nop 1
	v_addc_co_u32_e32 v183, vcc, -1, v101, vcc
	global_load_dwordx4 v[168:171], v[180:181], off nt
	global_load_dwordx4 v[172:175], v[182:183], off nt
	v_add_co_u32_e32 v180, vcc, 0xfffdc000, v100
	s_nop 1
	v_addc_co_u32_e32 v181, vcc, -1, v101, vcc
	global_load_dwordx4 v[176:179], v[180:181], off nt
	s_nop 0
	global_load_dwordx4 v[180:183], v[100:101], off nt
	s_mov_b64 s[8:9], 0x240000
	v_lshl_add_u64 v[100:101], v[100:101], 0, s[8:9]
	v_readlane_b32 s8, v1, 0
	s_waitcnt vmcnt(31)
	v_pk_fma_f32 v[24:25], v[114:115], s[8:9], v[24:25] op_sel_hi:[1,0,1]
	v_pk_fma_f32 v[22:23], v[112:113], s[8:9], v[22:23] op_sel_hi:[1,0,1]
	v_readlane_b32 s8, v104, 0
	s_nop 1
	v_pk_fma_f32 v[28:29], v[114:115], s[8:9], v[28:29] op_sel_hi:[1,0,1]
	v_pk_fma_f32 v[26:27], v[112:113], s[8:9], v[26:27] op_sel_hi:[1,0,1]
	v_readlane_b32 s8, v105, 0
	s_nop 1
	v_pk_fma_f32 v[32:33], v[114:115], s[8:9], v[32:33] op_sel_hi:[1,0,1]
	v_pk_fma_f32 v[30:31], v[112:113], s[8:9], v[30:31] op_sel_hi:[1,0,1]
	v_readlane_b32 s8, v106, 0
	s_nop 1
	v_pk_fma_f32 v[36:37], v[114:115], s[8:9], v[36:37] op_sel_hi:[1,0,1]
	v_pk_fma_f32 v[34:35], v[112:113], s[8:9], v[34:35] op_sel_hi:[1,0,1]
	v_readlane_b32 s8, v107, 0
	s_nop 1
	v_pk_fma_f32 v[40:41], v[114:115], s[8:9], v[40:41] op_sel_hi:[1,0,1]
	v_pk_fma_f32 v[38:39], v[112:113], s[8:9], v[38:39] op_sel_hi:[1,0,1]
	v_readlane_b32 s8, v108, 0
	s_nop 1
	v_pk_fma_f32 v[44:45], v[114:115], s[8:9], v[44:45] op_sel_hi:[1,0,1]
	v_pk_fma_f32 v[42:43], v[112:113], s[8:9], v[42:43] op_sel_hi:[1,0,1]
	v_readlane_b32 s8, v109, 0
	s_nop 1
	v_pk_fma_f32 v[52:53], v[114:115], s[8:9], v[52:53] op_sel_hi:[1,0,1]
	v_pk_fma_f32 v[50:51], v[112:113], s[8:9], v[50:51] op_sel_hi:[1,0,1]
	v_readlane_b32 s8, v110, 0
	s_nop 1
	v_pk_fma_f32 v[56:57], v[114:115], s[8:9], v[56:57] op_sel_hi:[1,0,1]
	v_pk_fma_f32 v[54:55], v[112:113], s[8:9], v[54:55] op_sel_hi:[1,0,1]
	v_readlane_b32 s8, v111, 0
	s_nop 1
	v_pk_fma_f32 v[60:61], v[114:115], s[8:9], v[60:61] op_sel_hi:[1,0,1]
	v_pk_fma_f32 v[58:59], v[112:113], s[8:9], v[58:59] op_sel_hi:[1,0,1]
	v_readlane_b32 s8, v1, 1
	s_waitcnt vmcnt(30)
	s_nop 0
	v_pk_fma_f32 v[24:25], v[118:119], s[8:9], v[24:25] op_sel_hi:[1,0,1]
	v_pk_fma_f32 v[22:23], v[116:117], s[8:9], v[22:23] op_sel_hi:[1,0,1]
	v_readlane_b32 s8, v104, 1
	s_nop 1
	v_pk_fma_f32 v[28:29], v[118:119], s[8:9], v[28:29] op_sel_hi:[1,0,1]
	v_pk_fma_f32 v[26:27], v[116:117], s[8:9], v[26:27] op_sel_hi:[1,0,1]
	v_readlane_b32 s8, v105, 1
	s_nop 1
	v_pk_fma_f32 v[32:33], v[118:119], s[8:9], v[32:33] op_sel_hi:[1,0,1]
	v_pk_fma_f32 v[30:31], v[116:117], s[8:9], v[30:31] op_sel_hi:[1,0,1]
	v_readlane_b32 s8, v106, 1
	s_nop 1
	v_pk_fma_f32 v[36:37], v[118:119], s[8:9], v[36:37] op_sel_hi:[1,0,1]
	v_pk_fma_f32 v[34:35], v[116:117], s[8:9], v[34:35] op_sel_hi:[1,0,1]
	v_readlane_b32 s8, v107, 1
	s_nop 1
	v_pk_fma_f32 v[40:41], v[118:119], s[8:9], v[40:41] op_sel_hi:[1,0,1]
	v_pk_fma_f32 v[38:39], v[116:117], s[8:9], v[38:39] op_sel_hi:[1,0,1]
	v_readlane_b32 s8, v108, 1
	s_nop 1
	v_pk_fma_f32 v[44:45], v[118:119], s[8:9], v[44:45] op_sel_hi:[1,0,1]
	v_pk_fma_f32 v[42:43], v[116:117], s[8:9], v[42:43] op_sel_hi:[1,0,1]
	v_readlane_b32 s8, v109, 1
	s_nop 1
	v_pk_fma_f32 v[52:53], v[118:119], s[8:9], v[52:53] op_sel_hi:[1,0,1]
	v_pk_fma_f32 v[50:51], v[116:117], s[8:9], v[50:51] op_sel_hi:[1,0,1]
	v_readlane_b32 s8, v110, 1
	s_nop 1
	v_pk_fma_f32 v[56:57], v[118:119], s[8:9], v[56:57] op_sel_hi:[1,0,1]
	v_pk_fma_f32 v[54:55], v[116:117], s[8:9], v[54:55] op_sel_hi:[1,0,1]
	v_readlane_b32 s8, v111, 1
	s_nop 0
	v_pk_fma_f32 v[60:61], v[118:119], s[8:9], v[60:61] op_sel_hi:[1,0,1]
	v_pk_fma_f32 v[58:59], v[116:117], s[8:9], v[58:59] op_sel_hi:[1,0,1]
	v_readlane_b32 s8, v1, 2
	s_waitcnt vmcnt(29)
	s_nop 0
	v_pk_fma_f32 v[24:25], v[92:93], s[8:9], v[24:25] op_sel_hi:[1,0,1]
	v_pk_fma_f32 v[22:23], v[90:91], s[8:9], v[22:23] op_sel_hi:[1,0,1]
	v_readlane_b32 s8, v104, 2
	s_nop 1
	v_pk_fma_f32 v[28:29], v[92:93], s[8:9], v[28:29] op_sel_hi:[1,0,1]
	v_pk_fma_f32 v[26:27], v[90:91], s[8:9], v[26:27] op_sel_hi:[1,0,1]
	v_readlane_b32 s8, v105, 2
	s_nop 1
	v_pk_fma_f32 v[32:33], v[92:93], s[8:9], v[32:33] op_sel_hi:[1,0,1]
	v_pk_fma_f32 v[30:31], v[90:91], s[8:9], v[30:31] op_sel_hi:[1,0,1]
	v_readlane_b32 s8, v106, 2
	s_nop 1
	v_pk_fma_f32 v[36:37], v[92:93], s[8:9], v[36:37] op_sel_hi:[1,0,1]
	v_pk_fma_f32 v[34:35], v[90:91], s[8:9], v[34:35] op_sel_hi:[1,0,1]
	v_readlane_b32 s8, v107, 2
	s_nop 1
	v_pk_fma_f32 v[40:41], v[92:93], s[8:9], v[40:41] op_sel_hi:[1,0,1]
	v_pk_fma_f32 v[38:39], v[90:91], s[8:9], v[38:39] op_sel_hi:[1,0,1]
	v_readlane_b32 s8, v108, 2
	s_nop 1
	v_pk_fma_f32 v[44:45], v[92:93], s[8:9], v[44:45] op_sel_hi:[1,0,1]
	v_pk_fma_f32 v[42:43], v[90:91], s[8:9], v[42:43] op_sel_hi:[1,0,1]
	v_readlane_b32 s8, v109, 2
	s_nop 1
	v_pk_fma_f32 v[52:53], v[92:93], s[8:9], v[52:53] op_sel_hi:[1,0,1]
	v_pk_fma_f32 v[50:51], v[90:91], s[8:9], v[50:51] op_sel_hi:[1,0,1]
	v_readlane_b32 s8, v110, 2
	s_nop 1
	v_pk_fma_f32 v[56:57], v[92:93], s[8:9], v[56:57] op_sel_hi:[1,0,1]
	v_pk_fma_f32 v[54:55], v[90:91], s[8:9], v[54:55] op_sel_hi:[1,0,1]
	v_readlane_b32 s8, v111, 2
	s_nop 0
	v_pk_fma_f32 v[60:61], v[92:93], s[8:9], v[60:61] op_sel_hi:[1,0,1]
	v_pk_fma_f32 v[58:59], v[90:91], s[8:9], v[58:59] op_sel_hi:[1,0,1]
	v_readlane_b32 s8, v1, 3
	s_waitcnt vmcnt(28)
	s_nop 0
	v_pk_fma_f32 v[24:25], v[88:89], s[8:9], v[24:25] op_sel_hi:[1,0,1]
	v_pk_fma_f32 v[22:23], v[86:87], s[8:9], v[22:23] op_sel_hi:[1,0,1]
	v_readlane_b32 s8, v104, 3
	s_nop 1
	v_pk_fma_f32 v[28:29], v[88:89], s[8:9], v[28:29] op_sel_hi:[1,0,1]
	v_pk_fma_f32 v[26:27], v[86:87], s[8:9], v[26:27] op_sel_hi:[1,0,1]
	v_readlane_b32 s8, v105, 3
	s_nop 1
	v_pk_fma_f32 v[32:33], v[88:89], s[8:9], v[32:33] op_sel_hi:[1,0,1]
	v_pk_fma_f32 v[30:31], v[86:87], s[8:9], v[30:31] op_sel_hi:[1,0,1]
	v_readlane_b32 s8, v106, 3
	s_nop 1
	v_pk_fma_f32 v[36:37], v[88:89], s[8:9], v[36:37] op_sel_hi:[1,0,1]
	v_pk_fma_f32 v[34:35], v[86:87], s[8:9], v[34:35] op_sel_hi:[1,0,1]
	v_readlane_b32 s8, v107, 3
	s_nop 1
	v_pk_fma_f32 v[40:41], v[88:89], s[8:9], v[40:41] op_sel_hi:[1,0,1]
	v_pk_fma_f32 v[38:39], v[86:87], s[8:9], v[38:39] op_sel_hi:[1,0,1]
	v_readlane_b32 s8, v108, 3
	s_nop 1
	v_pk_fma_f32 v[44:45], v[88:89], s[8:9], v[44:45] op_sel_hi:[1,0,1]
	v_pk_fma_f32 v[42:43], v[86:87], s[8:9], v[42:43] op_sel_hi:[1,0,1]
	v_readlane_b32 s8, v109, 3
	s_nop 1
	v_pk_fma_f32 v[52:53], v[88:89], s[8:9], v[52:53] op_sel_hi:[1,0,1]
	v_pk_fma_f32 v[50:51], v[86:87], s[8:9], v[50:51] op_sel_hi:[1,0,1]
	v_readlane_b32 s8, v110, 3
	s_nop 1
	v_pk_fma_f32 v[56:57], v[88:89], s[8:9], v[56:57] op_sel_hi:[1,0,1]
	v_pk_fma_f32 v[54:55], v[86:87], s[8:9], v[54:55] op_sel_hi:[1,0,1]
	v_readlane_b32 s8, v111, 3
	s_nop 0
	v_pk_fma_f32 v[60:61], v[88:89], s[8:9], v[60:61] op_sel_hi:[1,0,1]
	v_pk_fma_f32 v[58:59], v[86:87], s[8:9], v[58:59] op_sel_hi:[1,0,1]
	v_readlane_b32 s8, v1, 4
	s_waitcnt vmcnt(27)
	s_nop 0
	v_pk_fma_f32 v[24:25], v[84:85], s[8:9], v[24:25] op_sel_hi:[1,0,1]
	v_pk_fma_f32 v[22:23], v[82:83], s[8:9], v[22:23] op_sel_hi:[1,0,1]
	v_readlane_b32 s8, v104, 4
	s_nop 1
	v_pk_fma_f32 v[28:29], v[84:85], s[8:9], v[28:29] op_sel_hi:[1,0,1]
	v_pk_fma_f32 v[26:27], v[82:83], s[8:9], v[26:27] op_sel_hi:[1,0,1]
	v_readlane_b32 s8, v105, 4
	s_nop 1
	v_pk_fma_f32 v[32:33], v[84:85], s[8:9], v[32:33] op_sel_hi:[1,0,1]
	v_pk_fma_f32 v[30:31], v[82:83], s[8:9], v[30:31] op_sel_hi:[1,0,1]
	v_readlane_b32 s8, v106, 4
	s_nop 1
	v_pk_fma_f32 v[36:37], v[84:85], s[8:9], v[36:37] op_sel_hi:[1,0,1]
	v_pk_fma_f32 v[34:35], v[82:83], s[8:9], v[34:35] op_sel_hi:[1,0,1]
	v_readlane_b32 s8, v107, 4
	s_nop 1
	v_pk_fma_f32 v[40:41], v[84:85], s[8:9], v[40:41] op_sel_hi:[1,0,1]
	v_pk_fma_f32 v[38:39], v[82:83], s[8:9], v[38:39] op_sel_hi:[1,0,1]
	v_readlane_b32 s8, v108, 4
	s_nop 1
	v_pk_fma_f32 v[44:45], v[84:85], s[8:9], v[44:45] op_sel_hi:[1,0,1]
	v_pk_fma_f32 v[42:43], v[82:83], s[8:9], v[42:43] op_sel_hi:[1,0,1]
	v_readlane_b32 s8, v109, 4
	s_nop 1
	v_pk_fma_f32 v[52:53], v[84:85], s[8:9], v[52:53] op_sel_hi:[1,0,1]
	v_pk_fma_f32 v[50:51], v[82:83], s[8:9], v[50:51] op_sel_hi:[1,0,1]
	v_readlane_b32 s8, v110, 4
	s_nop 1
	v_pk_fma_f32 v[56:57], v[84:85], s[8:9], v[56:57] op_sel_hi:[1,0,1]
	v_pk_fma_f32 v[54:55], v[82:83], s[8:9], v[54:55] op_sel_hi:[1,0,1]
	v_readlane_b32 s8, v111, 4
	s_nop 0
	v_pk_fma_f32 v[60:61], v[84:85], s[8:9], v[60:61] op_sel_hi:[1,0,1]
	v_pk_fma_f32 v[58:59], v[82:83], s[8:9], v[58:59] op_sel_hi:[1,0,1]
	v_readlane_b32 s8, v1, 5
	s_waitcnt vmcnt(26)
	s_nop 0
	v_pk_fma_f32 v[24:25], v[80:81], s[8:9], v[24:25] op_sel_hi:[1,0,1]
	v_pk_fma_f32 v[22:23], v[78:79], s[8:9], v[22:23] op_sel_hi:[1,0,1]
	v_readlane_b32 s8, v104, 5
	s_nop 1
	v_pk_fma_f32 v[28:29], v[80:81], s[8:9], v[28:29] op_sel_hi:[1,0,1]
	v_pk_fma_f32 v[26:27], v[78:79], s[8:9], v[26:27] op_sel_hi:[1,0,1]
	v_readlane_b32 s8, v105, 5
	s_nop 1
	v_pk_fma_f32 v[32:33], v[80:81], s[8:9], v[32:33] op_sel_hi:[1,0,1]
	v_pk_fma_f32 v[30:31], v[78:79], s[8:9], v[30:31] op_sel_hi:[1,0,1]
	v_readlane_b32 s8, v106, 5
	s_nop 1
	v_pk_fma_f32 v[36:37], v[80:81], s[8:9], v[36:37] op_sel_hi:[1,0,1]
	v_pk_fma_f32 v[34:35], v[78:79], s[8:9], v[34:35] op_sel_hi:[1,0,1]
	v_readlane_b32 s8, v107, 5
	s_nop 1
	v_pk_fma_f32 v[40:41], v[80:81], s[8:9], v[40:41] op_sel_hi:[1,0,1]
	v_pk_fma_f32 v[38:39], v[78:79], s[8:9], v[38:39] op_sel_hi:[1,0,1]
	v_readlane_b32 s8, v108, 5
	s_nop 1
	v_pk_fma_f32 v[44:45], v[80:81], s[8:9], v[44:45] op_sel_hi:[1,0,1]
	v_pk_fma_f32 v[42:43], v[78:79], s[8:9], v[42:43] op_sel_hi:[1,0,1]
	v_readlane_b32 s8, v109, 5
	s_nop 1
	v_pk_fma_f32 v[52:53], v[80:81], s[8:9], v[52:53] op_sel_hi:[1,0,1]
	v_pk_fma_f32 v[50:51], v[78:79], s[8:9], v[50:51] op_sel_hi:[1,0,1]
	v_readlane_b32 s8, v110, 5
	s_nop 1
	v_pk_fma_f32 v[56:57], v[80:81], s[8:9], v[56:57] op_sel_hi:[1,0,1]
	v_pk_fma_f32 v[54:55], v[78:79], s[8:9], v[54:55] op_sel_hi:[1,0,1]
	v_readlane_b32 s8, v111, 5
	s_nop 0
	v_pk_fma_f32 v[60:61], v[80:81], s[8:9], v[60:61] op_sel_hi:[1,0,1]
	v_pk_fma_f32 v[58:59], v[78:79], s[8:9], v[58:59] op_sel_hi:[1,0,1]
	v_readlane_b32 s8, v1, 6
	s_waitcnt vmcnt(25)
	s_nop 0
	v_pk_fma_f32 v[24:25], v[76:77], s[8:9], v[24:25] op_sel_hi:[1,0,1]
	v_pk_fma_f32 v[22:23], v[74:75], s[8:9], v[22:23] op_sel_hi:[1,0,1]
	v_readlane_b32 s8, v104, 6
	s_nop 1
	v_pk_fma_f32 v[28:29], v[76:77], s[8:9], v[28:29] op_sel_hi:[1,0,1]
	v_pk_fma_f32 v[26:27], v[74:75], s[8:9], v[26:27] op_sel_hi:[1,0,1]
	v_readlane_b32 s8, v105, 6
	s_nop 1
	v_pk_fma_f32 v[32:33], v[76:77], s[8:9], v[32:33] op_sel_hi:[1,0,1]
	v_pk_fma_f32 v[30:31], v[74:75], s[8:9], v[30:31] op_sel_hi:[1,0,1]
	v_readlane_b32 s8, v106, 6
	s_nop 1
	v_pk_fma_f32 v[36:37], v[76:77], s[8:9], v[36:37] op_sel_hi:[1,0,1]
	v_pk_fma_f32 v[34:35], v[74:75], s[8:9], v[34:35] op_sel_hi:[1,0,1]
	v_readlane_b32 s8, v107, 6
	s_nop 1
	v_pk_fma_f32 v[40:41], v[76:77], s[8:9], v[40:41] op_sel_hi:[1,0,1]
	v_pk_fma_f32 v[38:39], v[74:75], s[8:9], v[38:39] op_sel_hi:[1,0,1]
	v_readlane_b32 s8, v108, 6
	s_nop 1
	v_pk_fma_f32 v[44:45], v[76:77], s[8:9], v[44:45] op_sel_hi:[1,0,1]
	v_pk_fma_f32 v[42:43], v[74:75], s[8:9], v[42:43] op_sel_hi:[1,0,1]
	v_readlane_b32 s8, v109, 6
	s_nop 1
	v_pk_fma_f32 v[52:53], v[76:77], s[8:9], v[52:53] op_sel_hi:[1,0,1]
	v_pk_fma_f32 v[50:51], v[74:75], s[8:9], v[50:51] op_sel_hi:[1,0,1]
	v_readlane_b32 s8, v110, 6
	s_nop 1
	v_pk_fma_f32 v[56:57], v[76:77], s[8:9], v[56:57] op_sel_hi:[1,0,1]
	v_pk_fma_f32 v[54:55], v[74:75], s[8:9], v[54:55] op_sel_hi:[1,0,1]
	v_readlane_b32 s8, v111, 6
	s_nop 0
	v_pk_fma_f32 v[60:61], v[76:77], s[8:9], v[60:61] op_sel_hi:[1,0,1]
	v_pk_fma_f32 v[58:59], v[74:75], s[8:9], v[58:59] op_sel_hi:[1,0,1]
	v_readlane_b32 s8, v1, 7
	s_waitcnt vmcnt(24)
	s_nop 0
	v_pk_fma_f32 v[24:25], v[72:73], s[8:9], v[24:25] op_sel_hi:[1,0,1]
	v_pk_fma_f32 v[22:23], v[70:71], s[8:9], v[22:23] op_sel_hi:[1,0,1]
	v_readlane_b32 s8, v104, 7
	s_nop 1
	v_pk_fma_f32 v[28:29], v[72:73], s[8:9], v[28:29] op_sel_hi:[1,0,1]
	v_pk_fma_f32 v[26:27], v[70:71], s[8:9], v[26:27] op_sel_hi:[1,0,1]
	v_readlane_b32 s8, v105, 7
	s_nop 1
	v_pk_fma_f32 v[32:33], v[72:73], s[8:9], v[32:33] op_sel_hi:[1,0,1]
	v_pk_fma_f32 v[30:31], v[70:71], s[8:9], v[30:31] op_sel_hi:[1,0,1]
	v_readlane_b32 s8, v106, 7
	s_nop 1
	v_pk_fma_f32 v[36:37], v[72:73], s[8:9], v[36:37] op_sel_hi:[1,0,1]
	v_pk_fma_f32 v[34:35], v[70:71], s[8:9], v[34:35] op_sel_hi:[1,0,1]
	v_readlane_b32 s8, v107, 7
	s_nop 1
	v_pk_fma_f32 v[40:41], v[72:73], s[8:9], v[40:41] op_sel_hi:[1,0,1]
	v_pk_fma_f32 v[38:39], v[70:71], s[8:9], v[38:39] op_sel_hi:[1,0,1]
	v_readlane_b32 s8, v108, 7
	s_nop 1
	v_pk_fma_f32 v[44:45], v[72:73], s[8:9], v[44:45] op_sel_hi:[1,0,1]
	v_pk_fma_f32 v[42:43], v[70:71], s[8:9], v[42:43] op_sel_hi:[1,0,1]
	v_readlane_b32 s8, v109, 7
	s_nop 1
	v_pk_fma_f32 v[52:53], v[72:73], s[8:9], v[52:53] op_sel_hi:[1,0,1]
	v_pk_fma_f32 v[50:51], v[70:71], s[8:9], v[50:51] op_sel_hi:[1,0,1]
	v_readlane_b32 s8, v110, 7
	s_nop 1
	v_pk_fma_f32 v[56:57], v[72:73], s[8:9], v[56:57] op_sel_hi:[1,0,1]
	v_pk_fma_f32 v[54:55], v[70:71], s[8:9], v[54:55] op_sel_hi:[1,0,1]
	v_readlane_b32 s8, v111, 7
	s_nop 0
	v_pk_fma_f32 v[60:61], v[72:73], s[8:9], v[60:61] op_sel_hi:[1,0,1]
	v_pk_fma_f32 v[58:59], v[70:71], s[8:9], v[58:59] op_sel_hi:[1,0,1]
	v_readlane_b32 s8, v1, 8
	s_waitcnt vmcnt(23)
	s_nop 0
	v_pk_fma_f32 v[24:25], v[68:69], s[8:9], v[24:25] op_sel_hi:[1,0,1]
	v_pk_fma_f32 v[22:23], v[66:67], s[8:9], v[22:23] op_sel_hi:[1,0,1]
	v_readlane_b32 s8, v104, 8
	s_nop 1
	v_pk_fma_f32 v[28:29], v[68:69], s[8:9], v[28:29] op_sel_hi:[1,0,1]
	v_pk_fma_f32 v[26:27], v[66:67], s[8:9], v[26:27] op_sel_hi:[1,0,1]
	v_readlane_b32 s8, v105, 8
	s_nop 1
	v_pk_fma_f32 v[32:33], v[68:69], s[8:9], v[32:33] op_sel_hi:[1,0,1]
	v_pk_fma_f32 v[30:31], v[66:67], s[8:9], v[30:31] op_sel_hi:[1,0,1]
	v_readlane_b32 s8, v106, 8
	s_nop 1
	v_pk_fma_f32 v[36:37], v[68:69], s[8:9], v[36:37] op_sel_hi:[1,0,1]
	v_pk_fma_f32 v[34:35], v[66:67], s[8:9], v[34:35] op_sel_hi:[1,0,1]
	v_readlane_b32 s8, v107, 8
	s_nop 1
	v_pk_fma_f32 v[40:41], v[68:69], s[8:9], v[40:41] op_sel_hi:[1,0,1]
	v_pk_fma_f32 v[38:39], v[66:67], s[8:9], v[38:39] op_sel_hi:[1,0,1]
	v_readlane_b32 s8, v108, 8
	s_nop 1
	v_pk_fma_f32 v[44:45], v[68:69], s[8:9], v[44:45] op_sel_hi:[1,0,1]
	v_pk_fma_f32 v[42:43], v[66:67], s[8:9], v[42:43] op_sel_hi:[1,0,1]
	v_readlane_b32 s8, v109, 8
	s_nop 1
	v_pk_fma_f32 v[52:53], v[68:69], s[8:9], v[52:53] op_sel_hi:[1,0,1]
	v_pk_fma_f32 v[50:51], v[66:67], s[8:9], v[50:51] op_sel_hi:[1,0,1]
	v_readlane_b32 s8, v110, 8
	s_nop 1
	v_pk_fma_f32 v[56:57], v[68:69], s[8:9], v[56:57] op_sel_hi:[1,0,1]
	v_pk_fma_f32 v[54:55], v[66:67], s[8:9], v[54:55] op_sel_hi:[1,0,1]
	v_readlane_b32 s8, v111, 8
	s_nop 0
	v_pk_fma_f32 v[60:61], v[68:69], s[8:9], v[60:61] op_sel_hi:[1,0,1]
	v_pk_fma_f32 v[58:59], v[66:67], s[8:9], v[58:59] op_sel_hi:[1,0,1]
	v_readlane_b32 s8, v1, 9
	s_waitcnt vmcnt(22)
	s_nop 0
	v_pk_fma_f32 v[24:25], v[64:65], s[8:9], v[24:25] op_sel_hi:[1,0,1]
	v_pk_fma_f32 v[22:23], v[62:63], s[8:9], v[22:23] op_sel_hi:[1,0,1]
	v_readlane_b32 s8, v104, 9
	s_nop 1
	v_pk_fma_f32 v[28:29], v[64:65], s[8:9], v[28:29] op_sel_hi:[1,0,1]
	v_pk_fma_f32 v[26:27], v[62:63], s[8:9], v[26:27] op_sel_hi:[1,0,1]
	v_readlane_b32 s8, v105, 9
	s_nop 1
	v_pk_fma_f32 v[32:33], v[64:65], s[8:9], v[32:33] op_sel_hi:[1,0,1]
	v_pk_fma_f32 v[30:31], v[62:63], s[8:9], v[30:31] op_sel_hi:[1,0,1]
	v_readlane_b32 s8, v106, 9
	s_nop 1
	v_pk_fma_f32 v[36:37], v[64:65], s[8:9], v[36:37] op_sel_hi:[1,0,1]
	v_pk_fma_f32 v[34:35], v[62:63], s[8:9], v[34:35] op_sel_hi:[1,0,1]
	v_readlane_b32 s8, v107, 9
	s_nop 1
	v_pk_fma_f32 v[40:41], v[64:65], s[8:9], v[40:41] op_sel_hi:[1,0,1]
	v_pk_fma_f32 v[38:39], v[62:63], s[8:9], v[38:39] op_sel_hi:[1,0,1]
	v_readlane_b32 s8, v108, 9
	s_nop 1
	v_pk_fma_f32 v[44:45], v[64:65], s[8:9], v[44:45] op_sel_hi:[1,0,1]
	v_pk_fma_f32 v[42:43], v[62:63], s[8:9], v[42:43] op_sel_hi:[1,0,1]
	v_readlane_b32 s8, v109, 9
	s_nop 1
	v_pk_fma_f32 v[52:53], v[64:65], s[8:9], v[52:53] op_sel_hi:[1,0,1]
	v_pk_fma_f32 v[50:51], v[62:63], s[8:9], v[50:51] op_sel_hi:[1,0,1]
	v_readlane_b32 s8, v110, 9
	s_nop 1
	v_pk_fma_f32 v[56:57], v[64:65], s[8:9], v[56:57] op_sel_hi:[1,0,1]
	v_pk_fma_f32 v[54:55], v[62:63], s[8:9], v[54:55] op_sel_hi:[1,0,1]
	v_readlane_b32 s8, v111, 9
	s_nop 0
	v_pk_fma_f32 v[60:61], v[64:65], s[8:9], v[60:61] op_sel_hi:[1,0,1]
	v_pk_fma_f32 v[58:59], v[62:63], s[8:9], v[58:59] op_sel_hi:[1,0,1]
	v_readlane_b32 s8, v1, 10
	s_waitcnt vmcnt(21)
	s_nop 0
	v_pk_fma_f32 v[24:25], v[48:49], s[8:9], v[24:25] op_sel_hi:[1,0,1]
	v_pk_fma_f32 v[22:23], v[46:47], s[8:9], v[22:23] op_sel_hi:[1,0,1]
	v_readlane_b32 s8, v104, 10
	s_nop 1
	v_pk_fma_f32 v[28:29], v[48:49], s[8:9], v[28:29] op_sel_hi:[1,0,1]
	v_pk_fma_f32 v[26:27], v[46:47], s[8:9], v[26:27] op_sel_hi:[1,0,1]
	v_readlane_b32 s8, v105, 10
	s_nop 1
	v_pk_fma_f32 v[32:33], v[48:49], s[8:9], v[32:33] op_sel_hi:[1,0,1]
	v_pk_fma_f32 v[30:31], v[46:47], s[8:9], v[30:31] op_sel_hi:[1,0,1]
	v_readlane_b32 s8, v106, 10
	s_nop 1
	v_pk_fma_f32 v[36:37], v[48:49], s[8:9], v[36:37] op_sel_hi:[1,0,1]
	v_pk_fma_f32 v[34:35], v[46:47], s[8:9], v[34:35] op_sel_hi:[1,0,1]
	v_readlane_b32 s8, v107, 10
	s_nop 1
	v_pk_fma_f32 v[40:41], v[48:49], s[8:9], v[40:41] op_sel_hi:[1,0,1]
	v_pk_fma_f32 v[38:39], v[46:47], s[8:9], v[38:39] op_sel_hi:[1,0,1]
	v_readlane_b32 s8, v108, 10
	s_nop 1
	v_pk_fma_f32 v[44:45], v[48:49], s[8:9], v[44:45] op_sel_hi:[1,0,1]
	v_pk_fma_f32 v[42:43], v[46:47], s[8:9], v[42:43] op_sel_hi:[1,0,1]
	v_readlane_b32 s8, v109, 10
	s_nop 1
	v_pk_fma_f32 v[52:53], v[48:49], s[8:9], v[52:53] op_sel_hi:[1,0,1]
	v_pk_fma_f32 v[50:51], v[46:47], s[8:9], v[50:51] op_sel_hi:[1,0,1]
	v_readlane_b32 s8, v110, 10
	s_nop 1
	v_pk_fma_f32 v[56:57], v[48:49], s[8:9], v[56:57] op_sel_hi:[1,0,1]
	v_pk_fma_f32 v[54:55], v[46:47], s[8:9], v[54:55] op_sel_hi:[1,0,1]
	v_readlane_b32 s8, v111, 10
	s_nop 0
	v_pk_fma_f32 v[48:49], v[48:49], s[8:9], v[60:61] op_sel_hi:[1,0,1]
	v_pk_fma_f32 v[46:47], v[46:47], s[8:9], v[58:59] op_sel_hi:[1,0,1]
	v_readlane_b32 s8, v1, 11
	s_waitcnt vmcnt(20)
	s_nop 0
	v_pk_fma_f32 v[24:25], v[20:21], s[8:9], v[24:25] op_sel_hi:[1,0,1]
	v_pk_fma_f32 v[22:23], v[18:19], s[8:9], v[22:23] op_sel_hi:[1,0,1]
	v_readlane_b32 s8, v104, 11
	s_nop 1
	v_pk_fma_f32 v[28:29], v[20:21], s[8:9], v[28:29] op_sel_hi:[1,0,1]
	v_pk_fma_f32 v[26:27], v[18:19], s[8:9], v[26:27] op_sel_hi:[1,0,1]
	v_readlane_b32 s8, v105, 11
	s_nop 1
	v_pk_fma_f32 v[32:33], v[20:21], s[8:9], v[32:33] op_sel_hi:[1,0,1]
	v_pk_fma_f32 v[30:31], v[18:19], s[8:9], v[30:31] op_sel_hi:[1,0,1]
	v_readlane_b32 s8, v106, 11
	s_nop 1
	v_pk_fma_f32 v[36:37], v[20:21], s[8:9], v[36:37] op_sel_hi:[1,0,1]
	v_pk_fma_f32 v[34:35], v[18:19], s[8:9], v[34:35] op_sel_hi:[1,0,1]
	v_readlane_b32 s8, v107, 11
	s_nop 1
	v_pk_fma_f32 v[40:41], v[20:21], s[8:9], v[40:41] op_sel_hi:[1,0,1]
	v_pk_fma_f32 v[38:39], v[18:19], s[8:9], v[38:39] op_sel_hi:[1,0,1]
	v_readlane_b32 s8, v108, 11
	s_nop 1
	v_pk_fma_f32 v[44:45], v[20:21], s[8:9], v[44:45] op_sel_hi:[1,0,1]
	v_pk_fma_f32 v[42:43], v[18:19], s[8:9], v[42:43] op_sel_hi:[1,0,1]
	v_readlane_b32 s8, v109, 11
	s_nop 1
	v_pk_fma_f32 v[52:53], v[20:21], s[8:9], v[52:53] op_sel_hi:[1,0,1]
	v_pk_fma_f32 v[50:51], v[18:19], s[8:9], v[50:51] op_sel_hi:[1,0,1]
	v_readlane_b32 s8, v110, 11
	s_nop 1
	v_pk_fma_f32 v[56:57], v[20:21], s[8:9], v[56:57] op_sel_hi:[1,0,1]
	v_pk_fma_f32 v[54:55], v[18:19], s[8:9], v[54:55] op_sel_hi:[1,0,1]
	v_readlane_b32 s8, v111, 11
	s_nop 0
	v_pk_fma_f32 v[20:21], v[20:21], s[8:9], v[48:49] op_sel_hi:[1,0,1]
	v_pk_fma_f32 v[18:19], v[18:19], s[8:9], v[46:47] op_sel_hi:[1,0,1]
	v_readlane_b32 s8, v1, 12
	s_waitcnt vmcnt(19)
	s_nop 0
	v_pk_fma_f32 v[24:25], v[16:17], s[8:9], v[24:25] op_sel_hi:[1,0,1]
	v_pk_fma_f32 v[22:23], v[14:15], s[8:9], v[22:23] op_sel_hi:[1,0,1]
	v_readlane_b32 s8, v104, 12
	s_nop 1
	v_pk_fma_f32 v[28:29], v[16:17], s[8:9], v[28:29] op_sel_hi:[1,0,1]
	v_pk_fma_f32 v[26:27], v[14:15], s[8:9], v[26:27] op_sel_hi:[1,0,1]
	v_readlane_b32 s8, v105, 12
	s_nop 1
	v_pk_fma_f32 v[32:33], v[16:17], s[8:9], v[32:33] op_sel_hi:[1,0,1]
	v_pk_fma_f32 v[30:31], v[14:15], s[8:9], v[30:31] op_sel_hi:[1,0,1]
	v_readlane_b32 s8, v106, 12
	s_nop 1
	v_pk_fma_f32 v[36:37], v[16:17], s[8:9], v[36:37] op_sel_hi:[1,0,1]
	v_pk_fma_f32 v[34:35], v[14:15], s[8:9], v[34:35] op_sel_hi:[1,0,1]
	v_readlane_b32 s8, v107, 12
	s_nop 1
	v_pk_fma_f32 v[40:41], v[16:17], s[8:9], v[40:41] op_sel_hi:[1,0,1]
	v_pk_fma_f32 v[38:39], v[14:15], s[8:9], v[38:39] op_sel_hi:[1,0,1]
	v_readlane_b32 s8, v108, 12
	s_nop 1
	v_pk_fma_f32 v[44:45], v[16:17], s[8:9], v[44:45] op_sel_hi:[1,0,1]
	v_pk_fma_f32 v[42:43], v[14:15], s[8:9], v[42:43] op_sel_hi:[1,0,1]
	v_readlane_b32 s8, v109, 12
	s_nop 1
	v_pk_fma_f32 v[46:47], v[16:17], s[8:9], v[52:53] op_sel_hi:[1,0,1]
	v_pk_fma_f32 v[48:49], v[14:15], s[8:9], v[50:51] op_sel_hi:[1,0,1]
	v_readlane_b32 s8, v110, 12
	s_nop 1
	v_pk_fma_f32 v[50:51], v[16:17], s[8:9], v[56:57] op_sel_hi:[1,0,1]
	v_pk_fma_f32 v[52:53], v[14:15], s[8:9], v[54:55] op_sel_hi:[1,0,1]
	v_readlane_b32 s8, v111, 12
	s_nop 0
	v_pk_fma_f32 v[16:17], v[16:17], s[8:9], v[20:21] op_sel_hi:[1,0,1]
	v_pk_fma_f32 v[14:15], v[14:15], s[8:9], v[18:19] op_sel_hi:[1,0,1]
	v_readlane_b32 s8, v1, 13
	s_waitcnt vmcnt(18)
	s_nop 0
	v_pk_fma_f32 v[18:19], v[12:13], s[8:9], v[24:25] op_sel_hi:[1,0,1]
	v_pk_fma_f32 v[20:21], v[10:11], s[8:9], v[22:23] op_sel_hi:[1,0,1]
	v_readlane_b32 s8, v104, 13
	s_nop 1
	v_pk_fma_f32 v[22:23], v[12:13], s[8:9], v[28:29] op_sel_hi:[1,0,1]
	v_pk_fma_f32 v[24:25], v[10:11], s[8:9], v[26:27] op_sel_hi:[1,0,1]
	v_readlane_b32 s8, v105, 13
	s_nop 1
	v_pk_fma_f32 v[26:27], v[12:13], s[8:9], v[32:33] op_sel_hi:[1,0,1]
	v_pk_fma_f32 v[28:29], v[10:11], s[8:9], v[30:31] op_sel_hi:[1,0,1]
	v_readlane_b32 s8, v106, 13
	s_nop 1
	v_pk_fma_f32 v[30:31], v[12:13], s[8:9], v[36:37] op_sel_hi:[1,0,1]
	v_pk_fma_f32 v[32:33], v[10:11], s[8:9], v[34:35] op_sel_hi:[1,0,1]
	v_readlane_b32 s8, v107, 13
	s_nop 1
	v_pk_fma_f32 v[34:35], v[12:13], s[8:9], v[40:41] op_sel_hi:[1,0,1]
	v_pk_fma_f32 v[36:37], v[10:11], s[8:9], v[38:39] op_sel_hi:[1,0,1]
	v_readlane_b32 s8, v108, 13
	s_nop 1
	v_pk_fma_f32 v[38:39], v[12:13], s[8:9], v[44:45] op_sel_hi:[1,0,1]
	v_pk_fma_f32 v[40:41], v[10:11], s[8:9], v[42:43] op_sel_hi:[1,0,1]
	v_readlane_b32 s8, v109, 13
	s_nop 1
	v_pk_fma_f32 v[42:43], v[12:13], s[8:9], v[46:47] op_sel_hi:[1,0,1]
	v_pk_fma_f32 v[44:45], v[10:11], s[8:9], v[48:49] op_sel_hi:[1,0,1]
	v_readlane_b32 s8, v110, 13
	s_nop 1
	v_pk_fma_f32 v[46:47], v[12:13], s[8:9], v[50:51] op_sel_hi:[1,0,1]
	v_pk_fma_f32 v[48:49], v[10:11], s[8:9], v[52:53] op_sel_hi:[1,0,1]
	v_readlane_b32 s8, v111, 13
	s_nop 0
	v_pk_fma_f32 v[12:13], v[12:13], s[8:9], v[16:17] op_sel_hi:[1,0,1]
	v_pk_fma_f32 v[10:11], v[10:11], s[8:9], v[14:15] op_sel_hi:[1,0,1]
	v_readlane_b32 s8, v1, 14
	s_waitcnt vmcnt(17)
	s_nop 0
	v_pk_fma_f32 v[14:15], v[8:9], s[8:9], v[18:19] op_sel_hi:[1,0,1]
	v_pk_fma_f32 v[16:17], v[6:7], s[8:9], v[20:21] op_sel_hi:[1,0,1]
	v_readlane_b32 s8, v104, 14
	s_nop 1
	v_pk_fma_f32 v[18:19], v[8:9], s[8:9], v[22:23] op_sel_hi:[1,0,1]
	v_pk_fma_f32 v[20:21], v[6:7], s[8:9], v[24:25] op_sel_hi:[1,0,1]
	v_readlane_b32 s8, v105, 14
	s_nop 1
	v_pk_fma_f32 v[50:51], v[8:9], s[8:9], v[26:27] op_sel_hi:[1,0,1]
	v_pk_fma_f32 v[52:53], v[6:7], s[8:9], v[28:29] op_sel_hi:[1,0,1]
	v_readlane_b32 s8, v106, 14
	s_nop 1
	v_pk_fma_f32 v[54:55], v[8:9], s[8:9], v[30:31] op_sel_hi:[1,0,1]
	v_pk_fma_f32 v[56:57], v[6:7], s[8:9], v[32:33] op_sel_hi:[1,0,1]
	v_readlane_b32 s8, v107, 14
	s_nop 1
	v_pk_fma_f32 v[58:59], v[8:9], s[8:9], v[34:35] op_sel_hi:[1,0,1]
	v_pk_fma_f32 v[60:61], v[6:7], s[8:9], v[36:37] op_sel_hi:[1,0,1]
	v_readlane_b32 s8, v108, 14
	s_nop 1
	v_pk_fma_f32 v[62:63], v[8:9], s[8:9], v[38:39] op_sel_hi:[1,0,1]
	v_pk_fma_f32 v[64:65], v[6:7], s[8:9], v[40:41] op_sel_hi:[1,0,1]
	v_readlane_b32 s8, v109, 14
	s_nop 1
	v_pk_fma_f32 v[66:67], v[8:9], s[8:9], v[42:43] op_sel_hi:[1,0,1]
	v_pk_fma_f32 v[68:69], v[6:7], s[8:9], v[44:45] op_sel_hi:[1,0,1]
	v_readlane_b32 s8, v110, 14
	s_nop 1
	v_pk_fma_f32 v[46:47], v[8:9], s[8:9], v[46:47] op_sel_hi:[1,0,1]
	v_pk_fma_f32 v[48:49], v[6:7], s[8:9], v[48:49] op_sel_hi:[1,0,1]
	v_readlane_b32 s8, v111, 14
	s_nop 0
	v_pk_fma_f32 v[8:9], v[8:9], s[8:9], v[12:13] op_sel_hi:[1,0,1]
	v_pk_fma_f32 v[6:7], v[6:7], s[8:9], v[10:11] op_sel_hi:[1,0,1]
	v_readlane_b32 s8, v1, 15
	s_waitcnt vmcnt(16)
	s_nop 0
	v_pk_fma_f32 v[24:25], v[4:5], s[8:9], v[14:15] op_sel_hi:[1,0,1]
	v_pk_fma_f32 v[22:23], v[2:3], s[8:9], v[16:17] op_sel_hi:[1,0,1]
	v_readlane_b32 s8, v104, 15
	s_nop 1
	v_pk_fma_f32 v[28:29], v[4:5], s[8:9], v[18:19] op_sel_hi:[1,0,1]
	v_pk_fma_f32 v[26:27], v[2:3], s[8:9], v[20:21] op_sel_hi:[1,0,1]
	v_readlane_b32 s8, v105, 15
	s_nop 1
	v_pk_fma_f32 v[32:33], v[4:5], s[8:9], v[50:51] op_sel_hi:[1,0,1]
	v_pk_fma_f32 v[30:31], v[2:3], s[8:9], v[52:53] op_sel_hi:[1,0,1]
	v_readlane_b32 s8, v106, 15
	s_nop 1
	v_pk_fma_f32 v[36:37], v[4:5], s[8:9], v[54:55] op_sel_hi:[1,0,1]
	v_pk_fma_f32 v[34:35], v[2:3], s[8:9], v[56:57] op_sel_hi:[1,0,1]
	v_readlane_b32 s8, v107, 15
	s_nop 1
	v_pk_fma_f32 v[40:41], v[4:5], s[8:9], v[58:59] op_sel_hi:[1,0,1]
	v_pk_fma_f32 v[38:39], v[2:3], s[8:9], v[60:61] op_sel_hi:[1,0,1]
	v_readlane_b32 s8, v108, 15
	s_nop 1
	v_pk_fma_f32 v[44:45], v[4:5], s[8:9], v[62:63] op_sel_hi:[1,0,1]
	v_pk_fma_f32 v[42:43], v[2:3], s[8:9], v[64:65] op_sel_hi:[1,0,1]
	v_readlane_b32 s8, v109, 15
	s_nop 1
	v_pk_fma_f32 v[52:53], v[4:5], s[8:9], v[66:67] op_sel_hi:[1,0,1]
	v_pk_fma_f32 v[50:51], v[2:3], s[8:9], v[68:69] op_sel_hi:[1,0,1]
	v_readlane_b32 s8, v110, 15
	s_nop 1
	v_pk_fma_f32 v[56:57], v[4:5], s[8:9], v[46:47] op_sel_hi:[1,0,1]
	v_pk_fma_f32 v[54:55], v[2:3], s[8:9], v[48:49] op_sel_hi:[1,0,1]
	v_readlane_b32 s8, v111, 15
	v_pk_fma_f32 v[60:61], v[4:5], s[8:9], v[8:9] op_sel_hi:[1,0,1]
	v_pk_fma_f32 v[58:59], v[2:3], s[8:9], v[6:7] op_sel_hi:[1,0,1]
	v_add_co_u32_e32 v2, vcc, 0xffde4000, v100
	s_nop 1
	v_addc_co_u32_e32 v3, vcc, -1, v101, vcc
	v_add_co_u32_e32 v4, vcc, 0xffe08000, v100
	s_nop 1
	v_addc_co_u32_e32 v5, vcc, -1, v101, vcc
	global_load_dwordx4 v[112:115], v[2:3], off nt
	global_load_dwordx4 v[116:119], v[4:5], off nt
	v_add_co_u32_e32 v2, vcc, 0xffe2c000, v100
	s_nop 1
	v_addc_co_u32_e32 v3, vcc, -1, v101, vcc
	v_add_co_u32_e32 v4, vcc, 0xffe50000, v100
	s_nop 1
	v_addc_co_u32_e32 v5, vcc, -1, v101, vcc
	global_load_dwordx4 v[90:93], v[2:3], off nt
	global_load_dwordx4 v[86:89], v[4:5], off nt
	v_add_co_u32_e32 v2, vcc, 0xffe74000, v100
	s_nop 1
	v_addc_co_u32_e32 v3, vcc, -1, v101, vcc
	v_add_co_u32_e32 v4, vcc, 0xffe98000, v100
	s_nop 1
	v_addc_co_u32_e32 v5, vcc, -1, v101, vcc
	global_load_dwordx4 v[82:85], v[2:3], off nt
	global_load_dwordx4 v[78:81], v[4:5], off nt
	v_add_co_u32_e32 v2, vcc, 0xffebc000, v100
	s_nop 1
	v_addc_co_u32_e32 v3, vcc, -1, v101, vcc
	v_add_co_u32_e32 v4, vcc, 0xffee0000, v100
	s_nop 1
	v_addc_co_u32_e32 v5, vcc, -1, v101, vcc
	global_load_dwordx4 v[74:77], v[2:3], off nt
	global_load_dwordx4 v[70:73], v[4:5], off nt
	v_add_co_u32_e32 v2, vcc, 0xfff04000, v100
	s_nop 1
	v_addc_co_u32_e32 v3, vcc, -1, v101, vcc
	v_add_co_u32_e32 v4, vcc, 0xfff28000, v100
	s_nop 1
	v_addc_co_u32_e32 v5, vcc, -1, v101, vcc
	global_load_dwordx4 v[66:69], v[2:3], off nt
	global_load_dwordx4 v[62:65], v[4:5], off nt
	v_add_co_u32_e32 v2, vcc, 0xfff4c000, v100
	s_nop 1
	v_addc_co_u32_e32 v3, vcc, -1, v101, vcc
	v_add_co_u32_e32 v4, vcc, 0xfff70000, v100
	s_nop 1
	v_addc_co_u32_e32 v5, vcc, -1, v101, vcc
	global_load_dwordx4 v[46:49], v[2:3], off nt
	global_load_dwordx4 v[18:21], v[4:5], off nt
	v_add_co_u32_e32 v2, vcc, 0xfff94000, v100
	s_nop 1
	v_addc_co_u32_e32 v3, vcc, -1, v101, vcc
	v_add_co_u32_e32 v4, vcc, 0xfffb8000, v100
	s_nop 1
	v_addc_co_u32_e32 v5, vcc, -1, v101, vcc
	global_load_dwordx4 v[14:17], v[2:3], off nt
	global_load_dwordx4 v[10:13], v[4:5], off nt
	v_add_co_u32_e32 v2, vcc, 0xfffdc000, v100
	s_nop 1
	v_addc_co_u32_e32 v3, vcc, -1, v101, vcc
	global_load_dwordx4 v[6:9], v[2:3], off nt
	s_nop 0
	global_load_dwordx4 v[2:5], v[100:101], off nt
	s_mov_b64 s[8:9], 0x240000
	v_lshl_add_u64 v[100:101], v[100:101], 0, s[8:9]
	v_readlane_b32 s8, v1, 16
	s_waitcnt vmcnt(31)
	v_pk_fma_f32 v[24:25], v[122:123], s[8:9], v[24:25] op_sel_hi:[1,0,1]
	v_pk_fma_f32 v[22:23], v[120:121], s[8:9], v[22:23] op_sel_hi:[1,0,1]
	v_readlane_b32 s8, v104, 16
	s_nop 1
	v_pk_fma_f32 v[28:29], v[122:123], s[8:9], v[28:29] op_sel_hi:[1,0,1]
	v_pk_fma_f32 v[26:27], v[120:121], s[8:9], v[26:27] op_sel_hi:[1,0,1]
	v_readlane_b32 s8, v105, 16
	s_nop 1
	v_pk_fma_f32 v[32:33], v[122:123], s[8:9], v[32:33] op_sel_hi:[1,0,1]
	v_pk_fma_f32 v[30:31], v[120:121], s[8:9], v[30:31] op_sel_hi:[1,0,1]
	v_readlane_b32 s8, v106, 16
	s_nop 1
	v_pk_fma_f32 v[36:37], v[122:123], s[8:9], v[36:37] op_sel_hi:[1,0,1]
	v_pk_fma_f32 v[34:35], v[120:121], s[8:9], v[34:35] op_sel_hi:[1,0,1]
	v_readlane_b32 s8, v107, 16
	s_nop 1
	v_pk_fma_f32 v[40:41], v[122:123], s[8:9], v[40:41] op_sel_hi:[1,0,1]
	v_pk_fma_f32 v[38:39], v[120:121], s[8:9], v[38:39] op_sel_hi:[1,0,1]
	v_readlane_b32 s8, v108, 16
	s_nop 1
	v_pk_fma_f32 v[44:45], v[122:123], s[8:9], v[44:45] op_sel_hi:[1,0,1]
	v_pk_fma_f32 v[42:43], v[120:121], s[8:9], v[42:43] op_sel_hi:[1,0,1]
	v_readlane_b32 s8, v109, 16
	s_nop 1
	v_pk_fma_f32 v[52:53], v[122:123], s[8:9], v[52:53] op_sel_hi:[1,0,1]
	v_pk_fma_f32 v[50:51], v[120:121], s[8:9], v[50:51] op_sel_hi:[1,0,1]
	v_readlane_b32 s8, v110, 16
	s_nop 1
	v_pk_fma_f32 v[56:57], v[122:123], s[8:9], v[56:57] op_sel_hi:[1,0,1]
	v_pk_fma_f32 v[54:55], v[120:121], s[8:9], v[54:55] op_sel_hi:[1,0,1]
	v_readlane_b32 s8, v111, 16
	s_nop 1
	v_pk_fma_f32 v[60:61], v[122:123], s[8:9], v[60:61] op_sel_hi:[1,0,1]
	v_pk_fma_f32 v[58:59], v[120:121], s[8:9], v[58:59] op_sel_hi:[1,0,1]
	v_readlane_b32 s8, v1, 17
	s_waitcnt vmcnt(30)
	s_nop 0
	v_pk_fma_f32 v[24:25], v[126:127], s[8:9], v[24:25] op_sel_hi:[1,0,1]
	v_pk_fma_f32 v[22:23], v[124:125], s[8:9], v[22:23] op_sel_hi:[1,0,1]
	v_readlane_b32 s8, v104, 17
	s_nop 1
	v_pk_fma_f32 v[28:29], v[126:127], s[8:9], v[28:29] op_sel_hi:[1,0,1]
	v_pk_fma_f32 v[26:27], v[124:125], s[8:9], v[26:27] op_sel_hi:[1,0,1]
	v_readlane_b32 s8, v105, 17
	s_nop 1
	v_pk_fma_f32 v[32:33], v[126:127], s[8:9], v[32:33] op_sel_hi:[1,0,1]
	v_pk_fma_f32 v[30:31], v[124:125], s[8:9], v[30:31] op_sel_hi:[1,0,1]
	v_readlane_b32 s8, v106, 17
	s_nop 1
	v_pk_fma_f32 v[36:37], v[126:127], s[8:9], v[36:37] op_sel_hi:[1,0,1]
	v_pk_fma_f32 v[34:35], v[124:125], s[8:9], v[34:35] op_sel_hi:[1,0,1]
	v_readlane_b32 s8, v107, 17
	s_nop 1
	v_pk_fma_f32 v[40:41], v[126:127], s[8:9], v[40:41] op_sel_hi:[1,0,1]
	v_pk_fma_f32 v[38:39], v[124:125], s[8:9], v[38:39] op_sel_hi:[1,0,1]
	v_readlane_b32 s8, v108, 17
	s_nop 1
	v_pk_fma_f32 v[44:45], v[126:127], s[8:9], v[44:45] op_sel_hi:[1,0,1]
	v_pk_fma_f32 v[42:43], v[124:125], s[8:9], v[42:43] op_sel_hi:[1,0,1]
	v_readlane_b32 s8, v109, 17
	s_nop 1
	v_pk_fma_f32 v[52:53], v[126:127], s[8:9], v[52:53] op_sel_hi:[1,0,1]
	v_pk_fma_f32 v[50:51], v[124:125], s[8:9], v[50:51] op_sel_hi:[1,0,1]
	v_readlane_b32 s8, v110, 17
	s_nop 1
	v_pk_fma_f32 v[56:57], v[126:127], s[8:9], v[56:57] op_sel_hi:[1,0,1]
	v_pk_fma_f32 v[54:55], v[124:125], s[8:9], v[54:55] op_sel_hi:[1,0,1]
	v_readlane_b32 s8, v111, 17
	s_nop 0
	v_pk_fma_f32 v[60:61], v[126:127], s[8:9], v[60:61] op_sel_hi:[1,0,1]
	v_pk_fma_f32 v[58:59], v[124:125], s[8:9], v[58:59] op_sel_hi:[1,0,1]
	v_readlane_b32 s8, v1, 18
	s_waitcnt vmcnt(29)
	s_nop 0
	v_pk_fma_f32 v[24:25], v[130:131], s[8:9], v[24:25] op_sel_hi:[1,0,1]
	v_pk_fma_f32 v[22:23], v[128:129], s[8:9], v[22:23] op_sel_hi:[1,0,1]
	v_readlane_b32 s8, v104, 18
	s_nop 1
	v_pk_fma_f32 v[28:29], v[130:131], s[8:9], v[28:29] op_sel_hi:[1,0,1]
	v_pk_fma_f32 v[26:27], v[128:129], s[8:9], v[26:27] op_sel_hi:[1,0,1]
	v_readlane_b32 s8, v105, 18
	s_nop 1
	v_pk_fma_f32 v[32:33], v[130:131], s[8:9], v[32:33] op_sel_hi:[1,0,1]
	v_pk_fma_f32 v[30:31], v[128:129], s[8:9], v[30:31] op_sel_hi:[1,0,1]
	v_readlane_b32 s8, v106, 18
	s_nop 1
	v_pk_fma_f32 v[36:37], v[130:131], s[8:9], v[36:37] op_sel_hi:[1,0,1]
	v_pk_fma_f32 v[34:35], v[128:129], s[8:9], v[34:35] op_sel_hi:[1,0,1]
	v_readlane_b32 s8, v107, 18
	s_nop 1
	v_pk_fma_f32 v[40:41], v[130:131], s[8:9], v[40:41] op_sel_hi:[1,0,1]
	v_pk_fma_f32 v[38:39], v[128:129], s[8:9], v[38:39] op_sel_hi:[1,0,1]
	v_readlane_b32 s8, v108, 18
	s_nop 1
	v_pk_fma_f32 v[44:45], v[130:131], s[8:9], v[44:45] op_sel_hi:[1,0,1]
	v_pk_fma_f32 v[42:43], v[128:129], s[8:9], v[42:43] op_sel_hi:[1,0,1]
	v_readlane_b32 s8, v109, 18
	s_nop 1
	v_pk_fma_f32 v[52:53], v[130:131], s[8:9], v[52:53] op_sel_hi:[1,0,1]
	v_pk_fma_f32 v[50:51], v[128:129], s[8:9], v[50:51] op_sel_hi:[1,0,1]
	v_readlane_b32 s8, v110, 18
	s_nop 1
	v_pk_fma_f32 v[56:57], v[130:131], s[8:9], v[56:57] op_sel_hi:[1,0,1]
	v_pk_fma_f32 v[54:55], v[128:129], s[8:9], v[54:55] op_sel_hi:[1,0,1]
	v_readlane_b32 s8, v111, 18
	s_nop 0
	v_pk_fma_f32 v[60:61], v[130:131], s[8:9], v[60:61] op_sel_hi:[1,0,1]
	v_pk_fma_f32 v[58:59], v[128:129], s[8:9], v[58:59] op_sel_hi:[1,0,1]
	v_readlane_b32 s8, v1, 19
	s_waitcnt vmcnt(28)
	s_nop 0
	v_pk_fma_f32 v[24:25], v[134:135], s[8:9], v[24:25] op_sel_hi:[1,0,1]
	v_pk_fma_f32 v[22:23], v[132:133], s[8:9], v[22:23] op_sel_hi:[1,0,1]
	v_readlane_b32 s8, v104, 19
	s_nop 1
	v_pk_fma_f32 v[28:29], v[134:135], s[8:9], v[28:29] op_sel_hi:[1,0,1]
	v_pk_fma_f32 v[26:27], v[132:133], s[8:9], v[26:27] op_sel_hi:[1,0,1]
	v_readlane_b32 s8, v105, 19
	s_nop 1
	v_pk_fma_f32 v[32:33], v[134:135], s[8:9], v[32:33] op_sel_hi:[1,0,1]
	v_pk_fma_f32 v[30:31], v[132:133], s[8:9], v[30:31] op_sel_hi:[1,0,1]
	v_readlane_b32 s8, v106, 19
	s_nop 1
	v_pk_fma_f32 v[36:37], v[134:135], s[8:9], v[36:37] op_sel_hi:[1,0,1]
	v_pk_fma_f32 v[34:35], v[132:133], s[8:9], v[34:35] op_sel_hi:[1,0,1]
	v_readlane_b32 s8, v107, 19
	s_nop 1
	v_pk_fma_f32 v[40:41], v[134:135], s[8:9], v[40:41] op_sel_hi:[1,0,1]
	v_pk_fma_f32 v[38:39], v[132:133], s[8:9], v[38:39] op_sel_hi:[1,0,1]
	v_readlane_b32 s8, v108, 19
	s_nop 1
	v_pk_fma_f32 v[44:45], v[134:135], s[8:9], v[44:45] op_sel_hi:[1,0,1]
	v_pk_fma_f32 v[42:43], v[132:133], s[8:9], v[42:43] op_sel_hi:[1,0,1]
	v_readlane_b32 s8, v109, 19
	s_nop 1
	v_pk_fma_f32 v[52:53], v[134:135], s[8:9], v[52:53] op_sel_hi:[1,0,1]
	v_pk_fma_f32 v[50:51], v[132:133], s[8:9], v[50:51] op_sel_hi:[1,0,1]
	v_readlane_b32 s8, v110, 19
	s_nop 1
	v_pk_fma_f32 v[56:57], v[134:135], s[8:9], v[56:57] op_sel_hi:[1,0,1]
	v_pk_fma_f32 v[54:55], v[132:133], s[8:9], v[54:55] op_sel_hi:[1,0,1]
	v_readlane_b32 s8, v111, 19
	s_nop 0
	v_pk_fma_f32 v[60:61], v[134:135], s[8:9], v[60:61] op_sel_hi:[1,0,1]
	v_pk_fma_f32 v[58:59], v[132:133], s[8:9], v[58:59] op_sel_hi:[1,0,1]
	v_readlane_b32 s8, v1, 20
	s_waitcnt vmcnt(27)
	s_nop 0
	v_pk_fma_f32 v[24:25], v[138:139], s[8:9], v[24:25] op_sel_hi:[1,0,1]
	v_pk_fma_f32 v[22:23], v[136:137], s[8:9], v[22:23] op_sel_hi:[1,0,1]
	v_readlane_b32 s8, v104, 20
	s_nop 1
	v_pk_fma_f32 v[28:29], v[138:139], s[8:9], v[28:29] op_sel_hi:[1,0,1]
	v_pk_fma_f32 v[26:27], v[136:137], s[8:9], v[26:27] op_sel_hi:[1,0,1]
	v_readlane_b32 s8, v105, 20
	s_nop 1
	v_pk_fma_f32 v[32:33], v[138:139], s[8:9], v[32:33] op_sel_hi:[1,0,1]
	v_pk_fma_f32 v[30:31], v[136:137], s[8:9], v[30:31] op_sel_hi:[1,0,1]
	v_readlane_b32 s8, v106, 20
	s_nop 1
	v_pk_fma_f32 v[36:37], v[138:139], s[8:9], v[36:37] op_sel_hi:[1,0,1]
	v_pk_fma_f32 v[34:35], v[136:137], s[8:9], v[34:35] op_sel_hi:[1,0,1]
	v_readlane_b32 s8, v107, 20
	s_nop 1
	v_pk_fma_f32 v[40:41], v[138:139], s[8:9], v[40:41] op_sel_hi:[1,0,1]
	v_pk_fma_f32 v[38:39], v[136:137], s[8:9], v[38:39] op_sel_hi:[1,0,1]
	v_readlane_b32 s8, v108, 20
	s_nop 1
	v_pk_fma_f32 v[44:45], v[138:139], s[8:9], v[44:45] op_sel_hi:[1,0,1]
	v_pk_fma_f32 v[42:43], v[136:137], s[8:9], v[42:43] op_sel_hi:[1,0,1]
	v_readlane_b32 s8, v109, 20
	s_nop 1
	v_pk_fma_f32 v[52:53], v[138:139], s[8:9], v[52:53] op_sel_hi:[1,0,1]
	v_pk_fma_f32 v[50:51], v[136:137], s[8:9], v[50:51] op_sel_hi:[1,0,1]
	v_readlane_b32 s8, v110, 20
	s_nop 1
	v_pk_fma_f32 v[56:57], v[138:139], s[8:9], v[56:57] op_sel_hi:[1,0,1]
	v_pk_fma_f32 v[54:55], v[136:137], s[8:9], v[54:55] op_sel_hi:[1,0,1]
	v_readlane_b32 s8, v111, 20
	s_nop 0
	v_pk_fma_f32 v[60:61], v[138:139], s[8:9], v[60:61] op_sel_hi:[1,0,1]
	v_pk_fma_f32 v[58:59], v[136:137], s[8:9], v[58:59] op_sel_hi:[1,0,1]
	v_readlane_b32 s8, v1, 21
	s_waitcnt vmcnt(26)
	s_nop 0
	v_pk_fma_f32 v[24:25], v[142:143], s[8:9], v[24:25] op_sel_hi:[1,0,1]
	v_pk_fma_f32 v[22:23], v[140:141], s[8:9], v[22:23] op_sel_hi:[1,0,1]
	v_readlane_b32 s8, v104, 21
	s_nop 1
	v_pk_fma_f32 v[28:29], v[142:143], s[8:9], v[28:29] op_sel_hi:[1,0,1]
	v_pk_fma_f32 v[26:27], v[140:141], s[8:9], v[26:27] op_sel_hi:[1,0,1]
	v_readlane_b32 s8, v105, 21
	s_nop 1
	v_pk_fma_f32 v[32:33], v[142:143], s[8:9], v[32:33] op_sel_hi:[1,0,1]
	v_pk_fma_f32 v[30:31], v[140:141], s[8:9], v[30:31] op_sel_hi:[1,0,1]
	v_readlane_b32 s8, v106, 21
	s_nop 1
	v_pk_fma_f32 v[36:37], v[142:143], s[8:9], v[36:37] op_sel_hi:[1,0,1]
	v_pk_fma_f32 v[34:35], v[140:141], s[8:9], v[34:35] op_sel_hi:[1,0,1]
	v_readlane_b32 s8, v107, 21
	s_nop 1
	v_pk_fma_f32 v[40:41], v[142:143], s[8:9], v[40:41] op_sel_hi:[1,0,1]
	v_pk_fma_f32 v[38:39], v[140:141], s[8:9], v[38:39] op_sel_hi:[1,0,1]
	v_readlane_b32 s8, v108, 21
	s_nop 1
	v_pk_fma_f32 v[44:45], v[142:143], s[8:9], v[44:45] op_sel_hi:[1,0,1]
	v_pk_fma_f32 v[42:43], v[140:141], s[8:9], v[42:43] op_sel_hi:[1,0,1]
	v_readlane_b32 s8, v109, 21
	s_nop 1
	v_pk_fma_f32 v[52:53], v[142:143], s[8:9], v[52:53] op_sel_hi:[1,0,1]
	v_pk_fma_f32 v[50:51], v[140:141], s[8:9], v[50:51] op_sel_hi:[1,0,1]
	v_readlane_b32 s8, v110, 21
	s_nop 1
	v_pk_fma_f32 v[56:57], v[142:143], s[8:9], v[56:57] op_sel_hi:[1,0,1]
	v_pk_fma_f32 v[54:55], v[140:141], s[8:9], v[54:55] op_sel_hi:[1,0,1]
	v_readlane_b32 s8, v111, 21
	s_nop 0
	v_pk_fma_f32 v[60:61], v[142:143], s[8:9], v[60:61] op_sel_hi:[1,0,1]
	v_pk_fma_f32 v[58:59], v[140:141], s[8:9], v[58:59] op_sel_hi:[1,0,1]
	v_readlane_b32 s8, v1, 22
	s_waitcnt vmcnt(25)
	s_nop 0
	v_pk_fma_f32 v[24:25], v[146:147], s[8:9], v[24:25] op_sel_hi:[1,0,1]
	v_pk_fma_f32 v[22:23], v[144:145], s[8:9], v[22:23] op_sel_hi:[1,0,1]
	v_readlane_b32 s8, v104, 22
	s_nop 1
	v_pk_fma_f32 v[28:29], v[146:147], s[8:9], v[28:29] op_sel_hi:[1,0,1]
	v_pk_fma_f32 v[26:27], v[144:145], s[8:9], v[26:27] op_sel_hi:[1,0,1]
	v_readlane_b32 s8, v105, 22
	s_nop 1
	v_pk_fma_f32 v[32:33], v[146:147], s[8:9], v[32:33] op_sel_hi:[1,0,1]
	v_pk_fma_f32 v[30:31], v[144:145], s[8:9], v[30:31] op_sel_hi:[1,0,1]
	v_readlane_b32 s8, v106, 22
	s_nop 1
	v_pk_fma_f32 v[36:37], v[146:147], s[8:9], v[36:37] op_sel_hi:[1,0,1]
	v_pk_fma_f32 v[34:35], v[144:145], s[8:9], v[34:35] op_sel_hi:[1,0,1]
	v_readlane_b32 s8, v107, 22
	s_nop 1
	v_pk_fma_f32 v[40:41], v[146:147], s[8:9], v[40:41] op_sel_hi:[1,0,1]
	v_pk_fma_f32 v[38:39], v[144:145], s[8:9], v[38:39] op_sel_hi:[1,0,1]
	v_readlane_b32 s8, v108, 22
	s_nop 1
	v_pk_fma_f32 v[44:45], v[146:147], s[8:9], v[44:45] op_sel_hi:[1,0,1]
	v_pk_fma_f32 v[42:43], v[144:145], s[8:9], v[42:43] op_sel_hi:[1,0,1]
	v_readlane_b32 s8, v109, 22
	s_nop 1
	v_pk_fma_f32 v[52:53], v[146:147], s[8:9], v[52:53] op_sel_hi:[1,0,1]
	v_pk_fma_f32 v[50:51], v[144:145], s[8:9], v[50:51] op_sel_hi:[1,0,1]
	v_readlane_b32 s8, v110, 22
	s_nop 1
	v_pk_fma_f32 v[56:57], v[146:147], s[8:9], v[56:57] op_sel_hi:[1,0,1]
	v_pk_fma_f32 v[54:55], v[144:145], s[8:9], v[54:55] op_sel_hi:[1,0,1]
	v_readlane_b32 s8, v111, 22
	s_nop 0
	v_pk_fma_f32 v[60:61], v[146:147], s[8:9], v[60:61] op_sel_hi:[1,0,1]
	v_pk_fma_f32 v[58:59], v[144:145], s[8:9], v[58:59] op_sel_hi:[1,0,1]
	v_readlane_b32 s8, v1, 23
	s_waitcnt vmcnt(24)
	s_nop 0
	v_pk_fma_f32 v[24:25], v[150:151], s[8:9], v[24:25] op_sel_hi:[1,0,1]
	v_pk_fma_f32 v[22:23], v[148:149], s[8:9], v[22:23] op_sel_hi:[1,0,1]
	v_readlane_b32 s8, v104, 23
	s_nop 1
	v_pk_fma_f32 v[28:29], v[150:151], s[8:9], v[28:29] op_sel_hi:[1,0,1]
	v_pk_fma_f32 v[26:27], v[148:149], s[8:9], v[26:27] op_sel_hi:[1,0,1]
	v_readlane_b32 s8, v105, 23
	s_nop 1
	v_pk_fma_f32 v[32:33], v[150:151], s[8:9], v[32:33] op_sel_hi:[1,0,1]
	v_pk_fma_f32 v[30:31], v[148:149], s[8:9], v[30:31] op_sel_hi:[1,0,1]
	v_readlane_b32 s8, v106, 23
	s_nop 1
	v_pk_fma_f32 v[36:37], v[150:151], s[8:9], v[36:37] op_sel_hi:[1,0,1]
	v_pk_fma_f32 v[34:35], v[148:149], s[8:9], v[34:35] op_sel_hi:[1,0,1]
	v_readlane_b32 s8, v107, 23
	s_nop 1
	v_pk_fma_f32 v[40:41], v[150:151], s[8:9], v[40:41] op_sel_hi:[1,0,1]
	v_pk_fma_f32 v[38:39], v[148:149], s[8:9], v[38:39] op_sel_hi:[1,0,1]
	v_readlane_b32 s8, v108, 23
	s_nop 1
	v_pk_fma_f32 v[44:45], v[150:151], s[8:9], v[44:45] op_sel_hi:[1,0,1]
	v_pk_fma_f32 v[42:43], v[148:149], s[8:9], v[42:43] op_sel_hi:[1,0,1]
	v_readlane_b32 s8, v109, 23
	s_nop 1
	v_pk_fma_f32 v[52:53], v[150:151], s[8:9], v[52:53] op_sel_hi:[1,0,1]
	v_pk_fma_f32 v[50:51], v[148:149], s[8:9], v[50:51] op_sel_hi:[1,0,1]
	v_readlane_b32 s8, v110, 23
	s_nop 1
	v_pk_fma_f32 v[56:57], v[150:151], s[8:9], v[56:57] op_sel_hi:[1,0,1]
	v_pk_fma_f32 v[54:55], v[148:149], s[8:9], v[54:55] op_sel_hi:[1,0,1]
	v_readlane_b32 s8, v111, 23
	s_nop 0
	v_pk_fma_f32 v[60:61], v[150:151], s[8:9], v[60:61] op_sel_hi:[1,0,1]
	v_pk_fma_f32 v[58:59], v[148:149], s[8:9], v[58:59] op_sel_hi:[1,0,1]
	v_readlane_b32 s8, v1, 24
	s_waitcnt vmcnt(23)
	s_nop 0
	v_pk_fma_f32 v[24:25], v[154:155], s[8:9], v[24:25] op_sel_hi:[1,0,1]
	v_pk_fma_f32 v[22:23], v[152:153], s[8:9], v[22:23] op_sel_hi:[1,0,1]
	v_readlane_b32 s8, v104, 24
	s_nop 1
	v_pk_fma_f32 v[28:29], v[154:155], s[8:9], v[28:29] op_sel_hi:[1,0,1]
	v_pk_fma_f32 v[26:27], v[152:153], s[8:9], v[26:27] op_sel_hi:[1,0,1]
	v_readlane_b32 s8, v105, 24
	s_nop 1
	v_pk_fma_f32 v[32:33], v[154:155], s[8:9], v[32:33] op_sel_hi:[1,0,1]
	v_pk_fma_f32 v[30:31], v[152:153], s[8:9], v[30:31] op_sel_hi:[1,0,1]
	v_readlane_b32 s8, v106, 24
	s_nop 1
	v_pk_fma_f32 v[36:37], v[154:155], s[8:9], v[36:37] op_sel_hi:[1,0,1]
	v_pk_fma_f32 v[34:35], v[152:153], s[8:9], v[34:35] op_sel_hi:[1,0,1]
	v_readlane_b32 s8, v107, 24
	s_nop 1
	v_pk_fma_f32 v[40:41], v[154:155], s[8:9], v[40:41] op_sel_hi:[1,0,1]
	v_pk_fma_f32 v[38:39], v[152:153], s[8:9], v[38:39] op_sel_hi:[1,0,1]
	v_readlane_b32 s8, v108, 24
	s_nop 1
	v_pk_fma_f32 v[44:45], v[154:155], s[8:9], v[44:45] op_sel_hi:[1,0,1]
	v_pk_fma_f32 v[42:43], v[152:153], s[8:9], v[42:43] op_sel_hi:[1,0,1]
	v_readlane_b32 s8, v109, 24
	s_nop 1
	v_pk_fma_f32 v[52:53], v[154:155], s[8:9], v[52:53] op_sel_hi:[1,0,1]
	v_pk_fma_f32 v[50:51], v[152:153], s[8:9], v[50:51] op_sel_hi:[1,0,1]
	v_readlane_b32 s8, v110, 24
	s_nop 1
	v_pk_fma_f32 v[56:57], v[154:155], s[8:9], v[56:57] op_sel_hi:[1,0,1]
	v_pk_fma_f32 v[54:55], v[152:153], s[8:9], v[54:55] op_sel_hi:[1,0,1]
	v_readlane_b32 s8, v111, 24
	s_nop 0
	v_pk_fma_f32 v[60:61], v[154:155], s[8:9], v[60:61] op_sel_hi:[1,0,1]
	v_pk_fma_f32 v[58:59], v[152:153], s[8:9], v[58:59] op_sel_hi:[1,0,1]
	v_readlane_b32 s8, v1, 25
	s_waitcnt vmcnt(22)
	s_nop 0
	v_pk_fma_f32 v[24:25], v[158:159], s[8:9], v[24:25] op_sel_hi:[1,0,1]
	v_pk_fma_f32 v[22:23], v[156:157], s[8:9], v[22:23] op_sel_hi:[1,0,1]
	v_readlane_b32 s8, v104, 25
	s_nop 1
	v_pk_fma_f32 v[28:29], v[158:159], s[8:9], v[28:29] op_sel_hi:[1,0,1]
	v_pk_fma_f32 v[26:27], v[156:157], s[8:9], v[26:27] op_sel_hi:[1,0,1]
	v_readlane_b32 s8, v105, 25
	s_nop 1
	v_pk_fma_f32 v[32:33], v[158:159], s[8:9], v[32:33] op_sel_hi:[1,0,1]
	v_pk_fma_f32 v[30:31], v[156:157], s[8:9], v[30:31] op_sel_hi:[1,0,1]
	v_readlane_b32 s8, v106, 25
	s_nop 1
	v_pk_fma_f32 v[36:37], v[158:159], s[8:9], v[36:37] op_sel_hi:[1,0,1]
	v_pk_fma_f32 v[34:35], v[156:157], s[8:9], v[34:35] op_sel_hi:[1,0,1]
	v_readlane_b32 s8, v107, 25
	s_nop 1
	v_pk_fma_f32 v[40:41], v[158:159], s[8:9], v[40:41] op_sel_hi:[1,0,1]
	v_pk_fma_f32 v[38:39], v[156:157], s[8:9], v[38:39] op_sel_hi:[1,0,1]
	v_readlane_b32 s8, v108, 25
	s_nop 1
	v_pk_fma_f32 v[44:45], v[158:159], s[8:9], v[44:45] op_sel_hi:[1,0,1]
	v_pk_fma_f32 v[42:43], v[156:157], s[8:9], v[42:43] op_sel_hi:[1,0,1]
	v_readlane_b32 s8, v109, 25
	s_nop 1
	v_pk_fma_f32 v[52:53], v[158:159], s[8:9], v[52:53] op_sel_hi:[1,0,1]
	v_pk_fma_f32 v[50:51], v[156:157], s[8:9], v[50:51] op_sel_hi:[1,0,1]
	v_readlane_b32 s8, v110, 25
	s_nop 1
	v_pk_fma_f32 v[56:57], v[158:159], s[8:9], v[56:57] op_sel_hi:[1,0,1]
	v_pk_fma_f32 v[54:55], v[156:157], s[8:9], v[54:55] op_sel_hi:[1,0,1]
	v_readlane_b32 s8, v111, 25
	s_nop 0
	v_pk_fma_f32 v[60:61], v[158:159], s[8:9], v[60:61] op_sel_hi:[1,0,1]
	v_pk_fma_f32 v[58:59], v[156:157], s[8:9], v[58:59] op_sel_hi:[1,0,1]
	v_readlane_b32 s8, v1, 26
	s_waitcnt vmcnt(21)
	s_nop 0
	v_pk_fma_f32 v[24:25], v[162:163], s[8:9], v[24:25] op_sel_hi:[1,0,1]
	v_pk_fma_f32 v[22:23], v[160:161], s[8:9], v[22:23] op_sel_hi:[1,0,1]
	v_readlane_b32 s8, v104, 26
	s_nop 1
	v_pk_fma_f32 v[28:29], v[162:163], s[8:9], v[28:29] op_sel_hi:[1,0,1]
	v_pk_fma_f32 v[26:27], v[160:161], s[8:9], v[26:27] op_sel_hi:[1,0,1]
	v_readlane_b32 s8, v105, 26
	s_nop 1
	v_pk_fma_f32 v[32:33], v[162:163], s[8:9], v[32:33] op_sel_hi:[1,0,1]
	v_pk_fma_f32 v[30:31], v[160:161], s[8:9], v[30:31] op_sel_hi:[1,0,1]
	v_readlane_b32 s8, v106, 26
	s_nop 1
	v_pk_fma_f32 v[36:37], v[162:163], s[8:9], v[36:37] op_sel_hi:[1,0,1]
	v_pk_fma_f32 v[34:35], v[160:161], s[8:9], v[34:35] op_sel_hi:[1,0,1]
	v_readlane_b32 s8, v107, 26
	s_nop 1
	v_pk_fma_f32 v[40:41], v[162:163], s[8:9], v[40:41] op_sel_hi:[1,0,1]
	v_pk_fma_f32 v[38:39], v[160:161], s[8:9], v[38:39] op_sel_hi:[1,0,1]
	v_readlane_b32 s8, v108, 26
	s_nop 1
	v_pk_fma_f32 v[44:45], v[162:163], s[8:9], v[44:45] op_sel_hi:[1,0,1]
	v_pk_fma_f32 v[42:43], v[160:161], s[8:9], v[42:43] op_sel_hi:[1,0,1]
	v_readlane_b32 s8, v109, 26
	s_nop 1
	v_pk_fma_f32 v[52:53], v[162:163], s[8:9], v[52:53] op_sel_hi:[1,0,1]
	v_pk_fma_f32 v[50:51], v[160:161], s[8:9], v[50:51] op_sel_hi:[1,0,1]
	v_readlane_b32 s8, v110, 26
	s_nop 1
	v_pk_fma_f32 v[56:57], v[162:163], s[8:9], v[56:57] op_sel_hi:[1,0,1]
	v_pk_fma_f32 v[54:55], v[160:161], s[8:9], v[54:55] op_sel_hi:[1,0,1]
	v_readlane_b32 s8, v111, 26
	s_nop 0
	v_pk_fma_f32 v[162:163], v[162:163], s[8:9], v[60:61] op_sel_hi:[1,0,1]
	v_pk_fma_f32 v[160:161], v[160:161], s[8:9], v[58:59] op_sel_hi:[1,0,1]
	v_readlane_b32 s8, v1, 27
	s_waitcnt vmcnt(20)
	s_nop 0
	v_pk_fma_f32 v[24:25], v[166:167], s[8:9], v[24:25] op_sel_hi:[1,0,1]
	v_pk_fma_f32 v[22:23], v[164:165], s[8:9], v[22:23] op_sel_hi:[1,0,1]
	v_readlane_b32 s8, v104, 27
	s_nop 1
	v_pk_fma_f32 v[28:29], v[166:167], s[8:9], v[28:29] op_sel_hi:[1,0,1]
	v_pk_fma_f32 v[26:27], v[164:165], s[8:9], v[26:27] op_sel_hi:[1,0,1]
	v_readlane_b32 s8, v105, 27
	s_nop 1
	v_pk_fma_f32 v[32:33], v[166:167], s[8:9], v[32:33] op_sel_hi:[1,0,1]
	v_pk_fma_f32 v[30:31], v[164:165], s[8:9], v[30:31] op_sel_hi:[1,0,1]
	v_readlane_b32 s8, v106, 27
	s_nop 1
	v_pk_fma_f32 v[36:37], v[166:167], s[8:9], v[36:37] op_sel_hi:[1,0,1]
	v_pk_fma_f32 v[34:35], v[164:165], s[8:9], v[34:35] op_sel_hi:[1,0,1]
	v_readlane_b32 s8, v107, 27
	s_nop 1
	v_pk_fma_f32 v[40:41], v[166:167], s[8:9], v[40:41] op_sel_hi:[1,0,1]
	v_pk_fma_f32 v[38:39], v[164:165], s[8:9], v[38:39] op_sel_hi:[1,0,1]
	v_readlane_b32 s8, v108, 27
	s_nop 1
	v_pk_fma_f32 v[44:45], v[166:167], s[8:9], v[44:45] op_sel_hi:[1,0,1]
	v_pk_fma_f32 v[42:43], v[164:165], s[8:9], v[42:43] op_sel_hi:[1,0,1]
	v_readlane_b32 s8, v109, 27
	s_nop 1
	v_pk_fma_f32 v[52:53], v[166:167], s[8:9], v[52:53] op_sel_hi:[1,0,1]
	v_pk_fma_f32 v[50:51], v[164:165], s[8:9], v[50:51] op_sel_hi:[1,0,1]
	v_readlane_b32 s8, v110, 27
	s_nop 1
	v_pk_fma_f32 v[56:57], v[166:167], s[8:9], v[56:57] op_sel_hi:[1,0,1]
	v_pk_fma_f32 v[54:55], v[164:165], s[8:9], v[54:55] op_sel_hi:[1,0,1]
	v_readlane_b32 s8, v111, 27
	s_nop 0
	v_pk_fma_f32 v[166:167], v[166:167], s[8:9], v[162:163] op_sel_hi:[1,0,1]
	v_pk_fma_f32 v[164:165], v[164:165], s[8:9], v[160:161] op_sel_hi:[1,0,1]
	v_readlane_b32 s8, v1, 28
	s_waitcnt vmcnt(19)
	s_nop 0
	v_pk_fma_f32 v[24:25], v[170:171], s[8:9], v[24:25] op_sel_hi:[1,0,1]
	v_pk_fma_f32 v[22:23], v[168:169], s[8:9], v[22:23] op_sel_hi:[1,0,1]
	v_readlane_b32 s8, v104, 28
	s_nop 1
	v_pk_fma_f32 v[28:29], v[170:171], s[8:9], v[28:29] op_sel_hi:[1,0,1]
	v_pk_fma_f32 v[26:27], v[168:169], s[8:9], v[26:27] op_sel_hi:[1,0,1]
	v_readlane_b32 s8, v105, 28
	s_nop 1
	v_pk_fma_f32 v[32:33], v[170:171], s[8:9], v[32:33] op_sel_hi:[1,0,1]
	v_pk_fma_f32 v[30:31], v[168:169], s[8:9], v[30:31] op_sel_hi:[1,0,1]
	v_readlane_b32 s8, v106, 28
	s_nop 1
	v_pk_fma_f32 v[36:37], v[170:171], s[8:9], v[36:37] op_sel_hi:[1,0,1]
	v_pk_fma_f32 v[34:35], v[168:169], s[8:9], v[34:35] op_sel_hi:[1,0,1]
	v_readlane_b32 s8, v107, 28
	s_nop 1
	v_pk_fma_f32 v[40:41], v[170:171], s[8:9], v[40:41] op_sel_hi:[1,0,1]
	v_pk_fma_f32 v[38:39], v[168:169], s[8:9], v[38:39] op_sel_hi:[1,0,1]
	v_readlane_b32 s8, v108, 28
	s_nop 1
	v_pk_fma_f32 v[44:45], v[170:171], s[8:9], v[44:45] op_sel_hi:[1,0,1]
	v_pk_fma_f32 v[42:43], v[168:169], s[8:9], v[42:43] op_sel_hi:[1,0,1]
	v_readlane_b32 s8, v109, 28
	s_nop 1
	v_pk_fma_f32 v[160:161], v[170:171], s[8:9], v[52:53] op_sel_hi:[1,0,1]
	v_pk_fma_f32 v[162:163], v[168:169], s[8:9], v[50:51] op_sel_hi:[1,0,1]
	v_readlane_b32 s8, v110, 28
	s_nop 1
	v_pk_fma_f32 v[50:51], v[170:171], s[8:9], v[56:57] op_sel_hi:[1,0,1]
	v_pk_fma_f32 v[52:53], v[168:169], s[8:9], v[54:55] op_sel_hi:[1,0,1]
	v_readlane_b32 s8, v111, 28
	s_nop 0
	v_pk_fma_f32 v[170:171], v[170:171], s[8:9], v[166:167] op_sel_hi:[1,0,1]
	v_pk_fma_f32 v[168:169], v[168:169], s[8:9], v[164:165] op_sel_hi:[1,0,1]
	v_readlane_b32 s8, v1, 29
	s_waitcnt vmcnt(18)
	s_nop 0
	v_pk_fma_f32 v[164:165], v[174:175], s[8:9], v[24:25] op_sel_hi:[1,0,1]
	v_pk_fma_f32 v[166:167], v[172:173], s[8:9], v[22:23] op_sel_hi:[1,0,1]
	v_readlane_b32 s8, v104, 29
	s_nop 1
	v_pk_fma_f32 v[22:23], v[174:175], s[8:9], v[28:29] op_sel_hi:[1,0,1]
	v_pk_fma_f32 v[24:25], v[172:173], s[8:9], v[26:27] op_sel_hi:[1,0,1]
	v_readlane_b32 s8, v105, 29
	s_nop 1
	v_pk_fma_f32 v[26:27], v[174:175], s[8:9], v[32:33] op_sel_hi:[1,0,1]
	v_pk_fma_f32 v[28:29], v[172:173], s[8:9], v[30:31] op_sel_hi:[1,0,1]
	v_readlane_b32 s8, v106, 29
	s_nop 1
	v_pk_fma_f32 v[30:31], v[174:175], s[8:9], v[36:37] op_sel_hi:[1,0,1]
	v_pk_fma_f32 v[32:33], v[172:173], s[8:9], v[34:35] op_sel_hi:[1,0,1]
	v_readlane_b32 s8, v107, 29
	s_nop 1
	v_pk_fma_f32 v[34:35], v[174:175], s[8:9], v[40:41] op_sel_hi:[1,0,1]
	v_pk_fma_f32 v[36:37], v[172:173], s[8:9], v[38:39] op_sel_hi:[1,0,1]
	v_readlane_b32 s8, v108, 29
	s_nop 1
	v_pk_fma_f32 v[38:39], v[174:175], s[8:9], v[44:45] op_sel_hi:[1,0,1]
	v_pk_fma_f32 v[40:41], v[172:173], s[8:9], v[42:43] op_sel_hi:[1,0,1]
	v_readlane_b32 s8, v109, 29
	s_nop 1
	v_pk_fma_f32 v[42:43], v[174:175], s[8:9], v[160:161] op_sel_hi:[1,0,1]
	v_pk_fma_f32 v[44:45], v[172:173], s[8:9], v[162:163] op_sel_hi:[1,0,1]
	v_readlane_b32 s8, v110, 29
	s_nop 1
	v_pk_fma_f32 v[160:161], v[174:175], s[8:9], v[50:51] op_sel_hi:[1,0,1]
	v_pk_fma_f32 v[162:163], v[172:173], s[8:9], v[52:53] op_sel_hi:[1,0,1]
	v_readlane_b32 s8, v111, 29
	s_nop 0
	v_pk_fma_f32 v[174:175], v[174:175], s[8:9], v[170:171] op_sel_hi:[1,0,1]
	v_pk_fma_f32 v[172:173], v[172:173], s[8:9], v[168:169] op_sel_hi:[1,0,1]
	v_readlane_b32 s8, v1, 30
	s_waitcnt vmcnt(17)
	s_nop 0
	v_pk_fma_f32 v[168:169], v[178:179], s[8:9], v[164:165] op_sel_hi:[1,0,1]
	v_pk_fma_f32 v[170:171], v[176:177], s[8:9], v[166:167] op_sel_hi:[1,0,1]
	v_readlane_b32 s8, v104, 30
	s_nop 1
	v_pk_fma_f32 v[164:165], v[178:179], s[8:9], v[22:23] op_sel_hi:[1,0,1]
	v_pk_fma_f32 v[166:167], v[176:177], s[8:9], v[24:25] op_sel_hi:[1,0,1]
	v_readlane_b32 s8, v105, 30
	s_nop 1
	v_pk_fma_f32 v[50:51], v[178:179], s[8:9], v[26:27] op_sel_hi:[1,0,1]
	v_pk_fma_f32 v[52:53], v[176:177], s[8:9], v[28:29] op_sel_hi:[1,0,1]
	v_readlane_b32 s8, v106, 30
	s_nop 1
	v_pk_fma_f32 v[54:55], v[178:179], s[8:9], v[30:31] op_sel_hi:[1,0,1]
	v_pk_fma_f32 v[56:57], v[176:177], s[8:9], v[32:33] op_sel_hi:[1,0,1]
	v_readlane_b32 s8, v107, 30
	s_nop 1
	v_pk_fma_f32 v[58:59], v[178:179], s[8:9], v[34:35] op_sel_hi:[1,0,1]
	v_pk_fma_f32 v[60:61], v[176:177], s[8:9], v[36:37] op_sel_hi:[1,0,1]
	v_readlane_b32 s8, v108, 30
	s_nop 1
	v_pk_fma_f32 v[156:157], v[178:179], s[8:9], v[38:39] op_sel_hi:[1,0,1]
	v_pk_fma_f32 v[158:159], v[176:177], s[8:9], v[40:41] op_sel_hi:[1,0,1]
	v_readlane_b32 s8, v109, 30
	s_nop 1
	v_pk_fma_f32 v[152:153], v[178:179], s[8:9], v[42:43] op_sel_hi:[1,0,1]
	v_pk_fma_f32 v[154:155], v[176:177], s[8:9], v[44:45] op_sel_hi:[1,0,1]
	v_readlane_b32 s8, v110, 30
	s_nop 1
	v_pk_fma_f32 v[160:161], v[178:179], s[8:9], v[160:161] op_sel_hi:[1,0,1]
	v_pk_fma_f32 v[162:163], v[176:177], s[8:9], v[162:163] op_sel_hi:[1,0,1]
	v_readlane_b32 s8, v111, 30
	s_nop 0
	v_pk_fma_f32 v[178:179], v[178:179], s[8:9], v[174:175] op_sel_hi:[1,0,1]
	v_pk_fma_f32 v[176:177], v[176:177], s[8:9], v[172:173] op_sel_hi:[1,0,1]
	v_readlane_b32 s8, v1, 31
	s_waitcnt vmcnt(16)
	s_nop 0
	v_pk_fma_f32 v[24:25], v[182:183], s[8:9], v[168:169] op_sel_hi:[1,0,1]
	v_pk_fma_f32 v[22:23], v[180:181], s[8:9], v[170:171] op_sel_hi:[1,0,1]
	v_readlane_b32 s8, v104, 31
	s_nop 1
	v_pk_fma_f32 v[28:29], v[182:183], s[8:9], v[164:165] op_sel_hi:[1,0,1]
	v_pk_fma_f32 v[26:27], v[180:181], s[8:9], v[166:167] op_sel_hi:[1,0,1]
	v_readlane_b32 s8, v105, 31
	s_nop 1
	v_pk_fma_f32 v[32:33], v[182:183], s[8:9], v[50:51] op_sel_hi:[1,0,1]
	v_pk_fma_f32 v[30:31], v[180:181], s[8:9], v[52:53] op_sel_hi:[1,0,1]
	v_readlane_b32 s8, v106, 31
	s_nop 1
	v_pk_fma_f32 v[36:37], v[182:183], s[8:9], v[54:55] op_sel_hi:[1,0,1]
	v_pk_fma_f32 v[34:35], v[180:181], s[8:9], v[56:57] op_sel_hi:[1,0,1]
	v_readlane_b32 s8, v107, 31
	s_nop 1
	v_pk_fma_f32 v[40:41], v[182:183], s[8:9], v[58:59] op_sel_hi:[1,0,1]
	v_pk_fma_f32 v[38:39], v[180:181], s[8:9], v[60:61] op_sel_hi:[1,0,1]
	v_readlane_b32 s8, v108, 31
	s_nop 1
	v_pk_fma_f32 v[44:45], v[182:183], s[8:9], v[156:157] op_sel_hi:[1,0,1]
	v_pk_fma_f32 v[42:43], v[180:181], s[8:9], v[158:159] op_sel_hi:[1,0,1]
	v_readlane_b32 s8, v109, 31
	s_nop 1
	v_pk_fma_f32 v[52:53], v[182:183], s[8:9], v[152:153] op_sel_hi:[1,0,1]
	v_pk_fma_f32 v[50:51], v[180:181], s[8:9], v[154:155] op_sel_hi:[1,0,1]
	v_readlane_b32 s8, v110, 31
	s_nop 1
	v_pk_fma_f32 v[56:57], v[182:183], s[8:9], v[160:161] op_sel_hi:[1,0,1]
	v_pk_fma_f32 v[54:55], v[180:181], s[8:9], v[162:163] op_sel_hi:[1,0,1]
	v_readlane_b32 s8, v111, 31
	v_pk_fma_f32 v[60:61], v[182:183], s[8:9], v[178:179] op_sel_hi:[1,0,1]
	v_pk_fma_f32 v[58:59], v[180:181], s[8:9], v[176:177] op_sel_hi:[1,0,1]
	v_add_co_u32_e32 v180, vcc, 0xffde4000, v100
	s_nop 1
	v_addc_co_u32_e32 v181, vcc, -1, v101, vcc
	v_add_co_u32_e32 v182, vcc, 0xffe08000, v100
	s_nop 1
	v_addc_co_u32_e32 v183, vcc, -1, v101, vcc
	global_load_dwordx4 v[120:123], v[180:181], off nt
	global_load_dwordx4 v[124:127], v[182:183], off nt
	v_add_co_u32_e32 v180, vcc, 0xffe2c000, v100
	s_nop 1
	v_addc_co_u32_e32 v181, vcc, -1, v101, vcc
	v_add_co_u32_e32 v182, vcc, 0xffe50000, v100
	s_nop 1
	v_addc_co_u32_e32 v183, vcc, -1, v101, vcc
	global_load_dwordx4 v[128:131], v[180:181], off nt
	global_load_dwordx4 v[132:135], v[182:183], off nt
	v_add_co_u32_e32 v180, vcc, 0xffe74000, v100
	s_nop 1
	v_addc_co_u32_e32 v181, vcc, -1, v101, vcc
	v_add_co_u32_e32 v182, vcc, 0xffe98000, v100
	s_nop 1
	v_addc_co_u32_e32 v183, vcc, -1, v101, vcc
	global_load_dwordx4 v[136:139], v[180:181], off nt
	global_load_dwordx4 v[140:143], v[182:183], off nt
	v_add_co_u32_e32 v180, vcc, 0xffebc000, v100
	s_nop 1
	v_addc_co_u32_e32 v181, vcc, -1, v101, vcc
	v_add_co_u32_e32 v182, vcc, 0xffee0000, v100
	s_nop 1
	v_addc_co_u32_e32 v183, vcc, -1, v101, vcc
	global_load_dwordx4 v[144:147], v[180:181], off nt
	global_load_dwordx4 v[148:151], v[182:183], off nt
	v_add_co_u32_e32 v180, vcc, 0xfff04000, v100
	s_nop 1
	v_addc_co_u32_e32 v181, vcc, -1, v101, vcc
	v_add_co_u32_e32 v182, vcc, 0xfff28000, v100
	s_nop 1
	v_addc_co_u32_e32 v183, vcc, -1, v101, vcc
	global_load_dwordx4 v[152:155], v[180:181], off nt
	global_load_dwordx4 v[156:159], v[182:183], off nt
	v_add_co_u32_e32 v180, vcc, 0xfff4c000, v100
	s_nop 1
	v_addc_co_u32_e32 v181, vcc, -1, v101, vcc
	v_add_co_u32_e32 v182, vcc, 0xfff70000, v100
	s_nop 1
	v_addc_co_u32_e32 v183, vcc, -1, v101, vcc
	global_load_dwordx4 v[160:163], v[180:181], off nt
	global_load_dwordx4 v[164:167], v[182:183], off nt
	v_add_co_u32_e32 v180, vcc, 0xfff94000, v100
	s_nop 1
	v_addc_co_u32_e32 v181, vcc, -1, v101, vcc
	v_add_co_u32_e32 v182, vcc, 0xfffb8000, v100
	s_nop 1
	v_addc_co_u32_e32 v183, vcc, -1, v101, vcc
	global_load_dwordx4 v[168:171], v[180:181], off nt
	global_load_dwordx4 v[172:175], v[182:183], off nt
	v_add_co_u32_e32 v180, vcc, 0xfffdc000, v100
	s_nop 1
	v_addc_co_u32_e32 v181, vcc, -1, v101, vcc
	global_load_dwordx4 v[176:179], v[180:181], off nt
	s_nop 0
	global_load_dwordx4 v[180:183], v[100:101], off nt
	s_mov_b64 s[8:9], 0x240000
	v_lshl_add_u64 v[100:101], v[100:101], 0, s[8:9]
	v_readlane_b32 s8, v1, 32
	s_waitcnt vmcnt(31)
	v_pk_fma_f32 v[24:25], v[114:115], s[8:9], v[24:25] op_sel_hi:[1,0,1]
	v_pk_fma_f32 v[22:23], v[112:113], s[8:9], v[22:23] op_sel_hi:[1,0,1]
	v_readlane_b32 s8, v104, 32
	s_nop 1
	v_pk_fma_f32 v[28:29], v[114:115], s[8:9], v[28:29] op_sel_hi:[1,0,1]
	v_pk_fma_f32 v[26:27], v[112:113], s[8:9], v[26:27] op_sel_hi:[1,0,1]
	v_readlane_b32 s8, v105, 32
	s_nop 1
	v_pk_fma_f32 v[32:33], v[114:115], s[8:9], v[32:33] op_sel_hi:[1,0,1]
	v_pk_fma_f32 v[30:31], v[112:113], s[8:9], v[30:31] op_sel_hi:[1,0,1]
	v_readlane_b32 s8, v106, 32
	s_nop 1
	v_pk_fma_f32 v[36:37], v[114:115], s[8:9], v[36:37] op_sel_hi:[1,0,1]
	v_pk_fma_f32 v[34:35], v[112:113], s[8:9], v[34:35] op_sel_hi:[1,0,1]
	v_readlane_b32 s8, v107, 32
	s_nop 1
	v_pk_fma_f32 v[40:41], v[114:115], s[8:9], v[40:41] op_sel_hi:[1,0,1]
	v_pk_fma_f32 v[38:39], v[112:113], s[8:9], v[38:39] op_sel_hi:[1,0,1]
	v_readlane_b32 s8, v108, 32
	s_nop 1
	v_pk_fma_f32 v[44:45], v[114:115], s[8:9], v[44:45] op_sel_hi:[1,0,1]
	v_pk_fma_f32 v[42:43], v[112:113], s[8:9], v[42:43] op_sel_hi:[1,0,1]
	v_readlane_b32 s8, v109, 32
	s_nop 1
	v_pk_fma_f32 v[52:53], v[114:115], s[8:9], v[52:53] op_sel_hi:[1,0,1]
	v_pk_fma_f32 v[50:51], v[112:113], s[8:9], v[50:51] op_sel_hi:[1,0,1]
	v_readlane_b32 s8, v110, 32
	s_nop 1
	v_pk_fma_f32 v[56:57], v[114:115], s[8:9], v[56:57] op_sel_hi:[1,0,1]
	v_pk_fma_f32 v[54:55], v[112:113], s[8:9], v[54:55] op_sel_hi:[1,0,1]
	v_readlane_b32 s8, v111, 32
	s_nop 1
	v_pk_fma_f32 v[60:61], v[114:115], s[8:9], v[60:61] op_sel_hi:[1,0,1]
	v_pk_fma_f32 v[58:59], v[112:113], s[8:9], v[58:59] op_sel_hi:[1,0,1]
	v_readlane_b32 s8, v1, 33
	s_waitcnt vmcnt(30)
	s_nop 0
	v_pk_fma_f32 v[24:25], v[118:119], s[8:9], v[24:25] op_sel_hi:[1,0,1]
	v_pk_fma_f32 v[22:23], v[116:117], s[8:9], v[22:23] op_sel_hi:[1,0,1]
	v_readlane_b32 s8, v104, 33
	s_nop 1
	v_pk_fma_f32 v[28:29], v[118:119], s[8:9], v[28:29] op_sel_hi:[1,0,1]
	v_pk_fma_f32 v[26:27], v[116:117], s[8:9], v[26:27] op_sel_hi:[1,0,1]
	v_readlane_b32 s8, v105, 33
	s_nop 1
	v_pk_fma_f32 v[32:33], v[118:119], s[8:9], v[32:33] op_sel_hi:[1,0,1]
	v_pk_fma_f32 v[30:31], v[116:117], s[8:9], v[30:31] op_sel_hi:[1,0,1]
	v_readlane_b32 s8, v106, 33
	s_nop 1
	v_pk_fma_f32 v[36:37], v[118:119], s[8:9], v[36:37] op_sel_hi:[1,0,1]
	v_pk_fma_f32 v[34:35], v[116:117], s[8:9], v[34:35] op_sel_hi:[1,0,1]
	v_readlane_b32 s8, v107, 33
	s_nop 1
	v_pk_fma_f32 v[40:41], v[118:119], s[8:9], v[40:41] op_sel_hi:[1,0,1]
	v_pk_fma_f32 v[38:39], v[116:117], s[8:9], v[38:39] op_sel_hi:[1,0,1]
	v_readlane_b32 s8, v108, 33
	s_nop 1
	v_pk_fma_f32 v[44:45], v[118:119], s[8:9], v[44:45] op_sel_hi:[1,0,1]
	v_pk_fma_f32 v[42:43], v[116:117], s[8:9], v[42:43] op_sel_hi:[1,0,1]
	v_readlane_b32 s8, v109, 33
	s_nop 1
	v_pk_fma_f32 v[52:53], v[118:119], s[8:9], v[52:53] op_sel_hi:[1,0,1]
	v_pk_fma_f32 v[50:51], v[116:117], s[8:9], v[50:51] op_sel_hi:[1,0,1]
	v_readlane_b32 s8, v110, 33
	s_nop 1
	v_pk_fma_f32 v[56:57], v[118:119], s[8:9], v[56:57] op_sel_hi:[1,0,1]
	v_pk_fma_f32 v[54:55], v[116:117], s[8:9], v[54:55] op_sel_hi:[1,0,1]
	v_readlane_b32 s8, v111, 33
	s_nop 0
	v_pk_fma_f32 v[60:61], v[118:119], s[8:9], v[60:61] op_sel_hi:[1,0,1]
	v_pk_fma_f32 v[58:59], v[116:117], s[8:9], v[58:59] op_sel_hi:[1,0,1]
	v_readlane_b32 s8, v1, 34
	s_waitcnt vmcnt(29)
	s_nop 0
	v_pk_fma_f32 v[24:25], v[92:93], s[8:9], v[24:25] op_sel_hi:[1,0,1]
	v_pk_fma_f32 v[22:23], v[90:91], s[8:9], v[22:23] op_sel_hi:[1,0,1]
	v_readlane_b32 s8, v104, 34
	s_nop 1
	v_pk_fma_f32 v[28:29], v[92:93], s[8:9], v[28:29] op_sel_hi:[1,0,1]
	v_pk_fma_f32 v[26:27], v[90:91], s[8:9], v[26:27] op_sel_hi:[1,0,1]
	v_readlane_b32 s8, v105, 34
	s_nop 1
	v_pk_fma_f32 v[32:33], v[92:93], s[8:9], v[32:33] op_sel_hi:[1,0,1]
	v_pk_fma_f32 v[30:31], v[90:91], s[8:9], v[30:31] op_sel_hi:[1,0,1]
	v_readlane_b32 s8, v106, 34
	s_nop 1
	v_pk_fma_f32 v[36:37], v[92:93], s[8:9], v[36:37] op_sel_hi:[1,0,1]
	v_pk_fma_f32 v[34:35], v[90:91], s[8:9], v[34:35] op_sel_hi:[1,0,1]
	v_readlane_b32 s8, v107, 34
	s_nop 1
	v_pk_fma_f32 v[40:41], v[92:93], s[8:9], v[40:41] op_sel_hi:[1,0,1]
	v_pk_fma_f32 v[38:39], v[90:91], s[8:9], v[38:39] op_sel_hi:[1,0,1]
	v_readlane_b32 s8, v108, 34
	s_nop 1
	v_pk_fma_f32 v[44:45], v[92:93], s[8:9], v[44:45] op_sel_hi:[1,0,1]
	v_pk_fma_f32 v[42:43], v[90:91], s[8:9], v[42:43] op_sel_hi:[1,0,1]
	v_readlane_b32 s8, v109, 34
	s_nop 1
	v_pk_fma_f32 v[52:53], v[92:93], s[8:9], v[52:53] op_sel_hi:[1,0,1]
	v_pk_fma_f32 v[50:51], v[90:91], s[8:9], v[50:51] op_sel_hi:[1,0,1]
	v_readlane_b32 s8, v110, 34
	s_nop 1
	v_pk_fma_f32 v[56:57], v[92:93], s[8:9], v[56:57] op_sel_hi:[1,0,1]
	v_pk_fma_f32 v[54:55], v[90:91], s[8:9], v[54:55] op_sel_hi:[1,0,1]
	v_readlane_b32 s8, v111, 34
	s_nop 0
	v_pk_fma_f32 v[60:61], v[92:93], s[8:9], v[60:61] op_sel_hi:[1,0,1]
	v_pk_fma_f32 v[58:59], v[90:91], s[8:9], v[58:59] op_sel_hi:[1,0,1]
	v_readlane_b32 s8, v1, 35
	s_waitcnt vmcnt(28)
	s_nop 0
	v_pk_fma_f32 v[24:25], v[88:89], s[8:9], v[24:25] op_sel_hi:[1,0,1]
	v_pk_fma_f32 v[22:23], v[86:87], s[8:9], v[22:23] op_sel_hi:[1,0,1]
	v_readlane_b32 s8, v104, 35
	s_nop 1
	v_pk_fma_f32 v[28:29], v[88:89], s[8:9], v[28:29] op_sel_hi:[1,0,1]
	v_pk_fma_f32 v[26:27], v[86:87], s[8:9], v[26:27] op_sel_hi:[1,0,1]
	v_readlane_b32 s8, v105, 35
	s_nop 1
	v_pk_fma_f32 v[32:33], v[88:89], s[8:9], v[32:33] op_sel_hi:[1,0,1]
	v_pk_fma_f32 v[30:31], v[86:87], s[8:9], v[30:31] op_sel_hi:[1,0,1]
	v_readlane_b32 s8, v106, 35
	s_nop 1
	v_pk_fma_f32 v[36:37], v[88:89], s[8:9], v[36:37] op_sel_hi:[1,0,1]
	v_pk_fma_f32 v[34:35], v[86:87], s[8:9], v[34:35] op_sel_hi:[1,0,1]
	v_readlane_b32 s8, v107, 35
	s_nop 1
	v_pk_fma_f32 v[40:41], v[88:89], s[8:9], v[40:41] op_sel_hi:[1,0,1]
	v_pk_fma_f32 v[38:39], v[86:87], s[8:9], v[38:39] op_sel_hi:[1,0,1]
	v_readlane_b32 s8, v108, 35
	s_nop 1
	v_pk_fma_f32 v[44:45], v[88:89], s[8:9], v[44:45] op_sel_hi:[1,0,1]
	v_pk_fma_f32 v[42:43], v[86:87], s[8:9], v[42:43] op_sel_hi:[1,0,1]
	v_readlane_b32 s8, v109, 35
	s_nop 1
	v_pk_fma_f32 v[52:53], v[88:89], s[8:9], v[52:53] op_sel_hi:[1,0,1]
	v_pk_fma_f32 v[50:51], v[86:87], s[8:9], v[50:51] op_sel_hi:[1,0,1]
	v_readlane_b32 s8, v110, 35
	s_nop 1
	v_pk_fma_f32 v[56:57], v[88:89], s[8:9], v[56:57] op_sel_hi:[1,0,1]
	v_pk_fma_f32 v[54:55], v[86:87], s[8:9], v[54:55] op_sel_hi:[1,0,1]
	v_readlane_b32 s8, v111, 35
	s_nop 0
	v_pk_fma_f32 v[60:61], v[88:89], s[8:9], v[60:61] op_sel_hi:[1,0,1]
	v_pk_fma_f32 v[58:59], v[86:87], s[8:9], v[58:59] op_sel_hi:[1,0,1]
	v_readlane_b32 s8, v1, 36
	s_waitcnt vmcnt(27)
	s_nop 0
	v_pk_fma_f32 v[24:25], v[84:85], s[8:9], v[24:25] op_sel_hi:[1,0,1]
	v_pk_fma_f32 v[22:23], v[82:83], s[8:9], v[22:23] op_sel_hi:[1,0,1]
	v_readlane_b32 s8, v104, 36
	s_nop 1
	v_pk_fma_f32 v[28:29], v[84:85], s[8:9], v[28:29] op_sel_hi:[1,0,1]
	v_pk_fma_f32 v[26:27], v[82:83], s[8:9], v[26:27] op_sel_hi:[1,0,1]
	v_readlane_b32 s8, v105, 36
	s_nop 1
	v_pk_fma_f32 v[32:33], v[84:85], s[8:9], v[32:33] op_sel_hi:[1,0,1]
	v_pk_fma_f32 v[30:31], v[82:83], s[8:9], v[30:31] op_sel_hi:[1,0,1]
	v_readlane_b32 s8, v106, 36
	s_nop 1
	v_pk_fma_f32 v[36:37], v[84:85], s[8:9], v[36:37] op_sel_hi:[1,0,1]
	v_pk_fma_f32 v[34:35], v[82:83], s[8:9], v[34:35] op_sel_hi:[1,0,1]
	v_readlane_b32 s8, v107, 36
	s_nop 1
	v_pk_fma_f32 v[40:41], v[84:85], s[8:9], v[40:41] op_sel_hi:[1,0,1]
	v_pk_fma_f32 v[38:39], v[82:83], s[8:9], v[38:39] op_sel_hi:[1,0,1]
	v_readlane_b32 s8, v108, 36
	s_nop 1
	v_pk_fma_f32 v[44:45], v[84:85], s[8:9], v[44:45] op_sel_hi:[1,0,1]
	v_pk_fma_f32 v[42:43], v[82:83], s[8:9], v[42:43] op_sel_hi:[1,0,1]
	v_readlane_b32 s8, v109, 36
	s_nop 1
	v_pk_fma_f32 v[52:53], v[84:85], s[8:9], v[52:53] op_sel_hi:[1,0,1]
	v_pk_fma_f32 v[50:51], v[82:83], s[8:9], v[50:51] op_sel_hi:[1,0,1]
	v_readlane_b32 s8, v110, 36
	s_nop 1
	v_pk_fma_f32 v[56:57], v[84:85], s[8:9], v[56:57] op_sel_hi:[1,0,1]
	v_pk_fma_f32 v[54:55], v[82:83], s[8:9], v[54:55] op_sel_hi:[1,0,1]
	v_readlane_b32 s8, v111, 36
	s_nop 0
	v_pk_fma_f32 v[60:61], v[84:85], s[8:9], v[60:61] op_sel_hi:[1,0,1]
	v_pk_fma_f32 v[58:59], v[82:83], s[8:9], v[58:59] op_sel_hi:[1,0,1]
	v_readlane_b32 s8, v1, 37
	s_waitcnt vmcnt(26)
	s_nop 0
	v_pk_fma_f32 v[24:25], v[80:81], s[8:9], v[24:25] op_sel_hi:[1,0,1]
	v_pk_fma_f32 v[22:23], v[78:79], s[8:9], v[22:23] op_sel_hi:[1,0,1]
	v_readlane_b32 s8, v104, 37
	s_nop 1
	v_pk_fma_f32 v[28:29], v[80:81], s[8:9], v[28:29] op_sel_hi:[1,0,1]
	v_pk_fma_f32 v[26:27], v[78:79], s[8:9], v[26:27] op_sel_hi:[1,0,1]
	v_readlane_b32 s8, v105, 37
	s_nop 1
	v_pk_fma_f32 v[32:33], v[80:81], s[8:9], v[32:33] op_sel_hi:[1,0,1]
	v_pk_fma_f32 v[30:31], v[78:79], s[8:9], v[30:31] op_sel_hi:[1,0,1]
	v_readlane_b32 s8, v106, 37
	s_nop 1
	v_pk_fma_f32 v[36:37], v[80:81], s[8:9], v[36:37] op_sel_hi:[1,0,1]
	v_pk_fma_f32 v[34:35], v[78:79], s[8:9], v[34:35] op_sel_hi:[1,0,1]
	v_readlane_b32 s8, v107, 37
	s_nop 1
	v_pk_fma_f32 v[40:41], v[80:81], s[8:9], v[40:41] op_sel_hi:[1,0,1]
	v_pk_fma_f32 v[38:39], v[78:79], s[8:9], v[38:39] op_sel_hi:[1,0,1]
	v_readlane_b32 s8, v108, 37
	s_nop 1
	v_pk_fma_f32 v[44:45], v[80:81], s[8:9], v[44:45] op_sel_hi:[1,0,1]
	v_pk_fma_f32 v[42:43], v[78:79], s[8:9], v[42:43] op_sel_hi:[1,0,1]
	v_readlane_b32 s8, v109, 37
	s_nop 1
	v_pk_fma_f32 v[52:53], v[80:81], s[8:9], v[52:53] op_sel_hi:[1,0,1]
	v_pk_fma_f32 v[50:51], v[78:79], s[8:9], v[50:51] op_sel_hi:[1,0,1]
	v_readlane_b32 s8, v110, 37
	s_nop 1
	v_pk_fma_f32 v[56:57], v[80:81], s[8:9], v[56:57] op_sel_hi:[1,0,1]
	v_pk_fma_f32 v[54:55], v[78:79], s[8:9], v[54:55] op_sel_hi:[1,0,1]
	v_readlane_b32 s8, v111, 37
	s_nop 0
	v_pk_fma_f32 v[60:61], v[80:81], s[8:9], v[60:61] op_sel_hi:[1,0,1]
	v_pk_fma_f32 v[58:59], v[78:79], s[8:9], v[58:59] op_sel_hi:[1,0,1]
	v_readlane_b32 s8, v1, 38
	s_waitcnt vmcnt(25)
	s_nop 0
	v_pk_fma_f32 v[24:25], v[76:77], s[8:9], v[24:25] op_sel_hi:[1,0,1]
	v_pk_fma_f32 v[22:23], v[74:75], s[8:9], v[22:23] op_sel_hi:[1,0,1]
	v_readlane_b32 s8, v104, 38
	s_nop 1
	v_pk_fma_f32 v[28:29], v[76:77], s[8:9], v[28:29] op_sel_hi:[1,0,1]
	v_pk_fma_f32 v[26:27], v[74:75], s[8:9], v[26:27] op_sel_hi:[1,0,1]
	v_readlane_b32 s8, v105, 38
	s_nop 1
	v_pk_fma_f32 v[32:33], v[76:77], s[8:9], v[32:33] op_sel_hi:[1,0,1]
	v_pk_fma_f32 v[30:31], v[74:75], s[8:9], v[30:31] op_sel_hi:[1,0,1]
	v_readlane_b32 s8, v106, 38
	s_nop 1
	v_pk_fma_f32 v[36:37], v[76:77], s[8:9], v[36:37] op_sel_hi:[1,0,1]
	v_pk_fma_f32 v[34:35], v[74:75], s[8:9], v[34:35] op_sel_hi:[1,0,1]
	v_readlane_b32 s8, v107, 38
	s_nop 1
	v_pk_fma_f32 v[40:41], v[76:77], s[8:9], v[40:41] op_sel_hi:[1,0,1]
	v_pk_fma_f32 v[38:39], v[74:75], s[8:9], v[38:39] op_sel_hi:[1,0,1]
	v_readlane_b32 s8, v108, 38
	s_nop 1
	v_pk_fma_f32 v[44:45], v[76:77], s[8:9], v[44:45] op_sel_hi:[1,0,1]
	v_pk_fma_f32 v[42:43], v[74:75], s[8:9], v[42:43] op_sel_hi:[1,0,1]
	v_readlane_b32 s8, v109, 38
	s_nop 1
	v_pk_fma_f32 v[52:53], v[76:77], s[8:9], v[52:53] op_sel_hi:[1,0,1]
	v_pk_fma_f32 v[50:51], v[74:75], s[8:9], v[50:51] op_sel_hi:[1,0,1]
	v_readlane_b32 s8, v110, 38
	s_nop 1
	v_pk_fma_f32 v[56:57], v[76:77], s[8:9], v[56:57] op_sel_hi:[1,0,1]
	v_pk_fma_f32 v[54:55], v[74:75], s[8:9], v[54:55] op_sel_hi:[1,0,1]
	v_readlane_b32 s8, v111, 38
	s_nop 0
	v_pk_fma_f32 v[60:61], v[76:77], s[8:9], v[60:61] op_sel_hi:[1,0,1]
	v_pk_fma_f32 v[58:59], v[74:75], s[8:9], v[58:59] op_sel_hi:[1,0,1]
	v_readlane_b32 s8, v1, 39
	s_waitcnt vmcnt(24)
	s_nop 0
	v_pk_fma_f32 v[24:25], v[72:73], s[8:9], v[24:25] op_sel_hi:[1,0,1]
	v_pk_fma_f32 v[22:23], v[70:71], s[8:9], v[22:23] op_sel_hi:[1,0,1]
	v_readlane_b32 s8, v104, 39
	s_nop 1
	v_pk_fma_f32 v[28:29], v[72:73], s[8:9], v[28:29] op_sel_hi:[1,0,1]
	v_pk_fma_f32 v[26:27], v[70:71], s[8:9], v[26:27] op_sel_hi:[1,0,1]
	v_readlane_b32 s8, v105, 39
	s_nop 1
	v_pk_fma_f32 v[32:33], v[72:73], s[8:9], v[32:33] op_sel_hi:[1,0,1]
	v_pk_fma_f32 v[30:31], v[70:71], s[8:9], v[30:31] op_sel_hi:[1,0,1]
	v_readlane_b32 s8, v106, 39
	s_nop 1
	v_pk_fma_f32 v[36:37], v[72:73], s[8:9], v[36:37] op_sel_hi:[1,0,1]
	v_pk_fma_f32 v[34:35], v[70:71], s[8:9], v[34:35] op_sel_hi:[1,0,1]
	v_readlane_b32 s8, v107, 39
	s_nop 1
	v_pk_fma_f32 v[40:41], v[72:73], s[8:9], v[40:41] op_sel_hi:[1,0,1]
	v_pk_fma_f32 v[38:39], v[70:71], s[8:9], v[38:39] op_sel_hi:[1,0,1]
	v_readlane_b32 s8, v108, 39
	s_nop 1
	v_pk_fma_f32 v[44:45], v[72:73], s[8:9], v[44:45] op_sel_hi:[1,0,1]
	v_pk_fma_f32 v[42:43], v[70:71], s[8:9], v[42:43] op_sel_hi:[1,0,1]
	v_readlane_b32 s8, v109, 39
	s_nop 1
	v_pk_fma_f32 v[52:53], v[72:73], s[8:9], v[52:53] op_sel_hi:[1,0,1]
	v_pk_fma_f32 v[50:51], v[70:71], s[8:9], v[50:51] op_sel_hi:[1,0,1]
	v_readlane_b32 s8, v110, 39
	s_nop 1
	v_pk_fma_f32 v[56:57], v[72:73], s[8:9], v[56:57] op_sel_hi:[1,0,1]
	v_pk_fma_f32 v[54:55], v[70:71], s[8:9], v[54:55] op_sel_hi:[1,0,1]
	v_readlane_b32 s8, v111, 39
	s_nop 0
	v_pk_fma_f32 v[60:61], v[72:73], s[8:9], v[60:61] op_sel_hi:[1,0,1]
	v_pk_fma_f32 v[58:59], v[70:71], s[8:9], v[58:59] op_sel_hi:[1,0,1]
	v_readlane_b32 s8, v1, 40
	s_waitcnt vmcnt(23)
	s_nop 0
	v_pk_fma_f32 v[24:25], v[68:69], s[8:9], v[24:25] op_sel_hi:[1,0,1]
	v_pk_fma_f32 v[22:23], v[66:67], s[8:9], v[22:23] op_sel_hi:[1,0,1]
	v_readlane_b32 s8, v104, 40
	s_nop 1
	v_pk_fma_f32 v[28:29], v[68:69], s[8:9], v[28:29] op_sel_hi:[1,0,1]
	v_pk_fma_f32 v[26:27], v[66:67], s[8:9], v[26:27] op_sel_hi:[1,0,1]
	v_readlane_b32 s8, v105, 40
	s_nop 1
	v_pk_fma_f32 v[32:33], v[68:69], s[8:9], v[32:33] op_sel_hi:[1,0,1]
	v_pk_fma_f32 v[30:31], v[66:67], s[8:9], v[30:31] op_sel_hi:[1,0,1]
	v_readlane_b32 s8, v106, 40
	s_nop 1
	v_pk_fma_f32 v[36:37], v[68:69], s[8:9], v[36:37] op_sel_hi:[1,0,1]
	v_pk_fma_f32 v[34:35], v[66:67], s[8:9], v[34:35] op_sel_hi:[1,0,1]
	v_readlane_b32 s8, v107, 40
	s_nop 1
	v_pk_fma_f32 v[40:41], v[68:69], s[8:9], v[40:41] op_sel_hi:[1,0,1]
	v_pk_fma_f32 v[38:39], v[66:67], s[8:9], v[38:39] op_sel_hi:[1,0,1]
	v_readlane_b32 s8, v108, 40
	s_nop 1
	v_pk_fma_f32 v[44:45], v[68:69], s[8:9], v[44:45] op_sel_hi:[1,0,1]
	v_pk_fma_f32 v[42:43], v[66:67], s[8:9], v[42:43] op_sel_hi:[1,0,1]
	v_readlane_b32 s8, v109, 40
	s_nop 1
	v_pk_fma_f32 v[52:53], v[68:69], s[8:9], v[52:53] op_sel_hi:[1,0,1]
	v_pk_fma_f32 v[50:51], v[66:67], s[8:9], v[50:51] op_sel_hi:[1,0,1]
	v_readlane_b32 s8, v110, 40
	s_nop 1
	v_pk_fma_f32 v[56:57], v[68:69], s[8:9], v[56:57] op_sel_hi:[1,0,1]
	v_pk_fma_f32 v[54:55], v[66:67], s[8:9], v[54:55] op_sel_hi:[1,0,1]
	v_readlane_b32 s8, v111, 40
	s_nop 0
	v_pk_fma_f32 v[60:61], v[68:69], s[8:9], v[60:61] op_sel_hi:[1,0,1]
	v_pk_fma_f32 v[58:59], v[66:67], s[8:9], v[58:59] op_sel_hi:[1,0,1]
	v_readlane_b32 s8, v1, 41
	s_waitcnt vmcnt(22)
	s_nop 0
	v_pk_fma_f32 v[24:25], v[64:65], s[8:9], v[24:25] op_sel_hi:[1,0,1]
	v_pk_fma_f32 v[22:23], v[62:63], s[8:9], v[22:23] op_sel_hi:[1,0,1]
	v_readlane_b32 s8, v104, 41
	s_nop 1
	v_pk_fma_f32 v[28:29], v[64:65], s[8:9], v[28:29] op_sel_hi:[1,0,1]
	v_pk_fma_f32 v[26:27], v[62:63], s[8:9], v[26:27] op_sel_hi:[1,0,1]
	v_readlane_b32 s8, v105, 41
	s_nop 1
	v_pk_fma_f32 v[32:33], v[64:65], s[8:9], v[32:33] op_sel_hi:[1,0,1]
	v_pk_fma_f32 v[30:31], v[62:63], s[8:9], v[30:31] op_sel_hi:[1,0,1]
	v_readlane_b32 s8, v106, 41
	s_nop 1
	v_pk_fma_f32 v[36:37], v[64:65], s[8:9], v[36:37] op_sel_hi:[1,0,1]
	v_pk_fma_f32 v[34:35], v[62:63], s[8:9], v[34:35] op_sel_hi:[1,0,1]
	v_readlane_b32 s8, v107, 41
	s_nop 1
	v_pk_fma_f32 v[40:41], v[64:65], s[8:9], v[40:41] op_sel_hi:[1,0,1]
	v_pk_fma_f32 v[38:39], v[62:63], s[8:9], v[38:39] op_sel_hi:[1,0,1]
	v_readlane_b32 s8, v108, 41
	s_nop 1
	v_pk_fma_f32 v[44:45], v[64:65], s[8:9], v[44:45] op_sel_hi:[1,0,1]
	v_pk_fma_f32 v[42:43], v[62:63], s[8:9], v[42:43] op_sel_hi:[1,0,1]
	v_readlane_b32 s8, v109, 41
	s_nop 1
	v_pk_fma_f32 v[52:53], v[64:65], s[8:9], v[52:53] op_sel_hi:[1,0,1]
	v_pk_fma_f32 v[50:51], v[62:63], s[8:9], v[50:51] op_sel_hi:[1,0,1]
	v_readlane_b32 s8, v110, 41
	s_nop 1
	v_pk_fma_f32 v[56:57], v[64:65], s[8:9], v[56:57] op_sel_hi:[1,0,1]
	v_pk_fma_f32 v[54:55], v[62:63], s[8:9], v[54:55] op_sel_hi:[1,0,1]
	v_readlane_b32 s8, v111, 41
	s_nop 0
	v_pk_fma_f32 v[60:61], v[64:65], s[8:9], v[60:61] op_sel_hi:[1,0,1]
	v_pk_fma_f32 v[58:59], v[62:63], s[8:9], v[58:59] op_sel_hi:[1,0,1]
	v_readlane_b32 s8, v1, 42
	s_waitcnt vmcnt(21)
	s_nop 0
	v_pk_fma_f32 v[24:25], v[48:49], s[8:9], v[24:25] op_sel_hi:[1,0,1]
	v_pk_fma_f32 v[22:23], v[46:47], s[8:9], v[22:23] op_sel_hi:[1,0,1]
	v_readlane_b32 s8, v104, 42
	s_nop 1
	v_pk_fma_f32 v[28:29], v[48:49], s[8:9], v[28:29] op_sel_hi:[1,0,1]
	v_pk_fma_f32 v[26:27], v[46:47], s[8:9], v[26:27] op_sel_hi:[1,0,1]
	v_readlane_b32 s8, v105, 42
	s_nop 1
	v_pk_fma_f32 v[32:33], v[48:49], s[8:9], v[32:33] op_sel_hi:[1,0,1]
	v_pk_fma_f32 v[30:31], v[46:47], s[8:9], v[30:31] op_sel_hi:[1,0,1]
	v_readlane_b32 s8, v106, 42
	s_nop 1
	v_pk_fma_f32 v[36:37], v[48:49], s[8:9], v[36:37] op_sel_hi:[1,0,1]
	v_pk_fma_f32 v[34:35], v[46:47], s[8:9], v[34:35] op_sel_hi:[1,0,1]
	v_readlane_b32 s8, v107, 42
	s_nop 1
	v_pk_fma_f32 v[40:41], v[48:49], s[8:9], v[40:41] op_sel_hi:[1,0,1]
	v_pk_fma_f32 v[38:39], v[46:47], s[8:9], v[38:39] op_sel_hi:[1,0,1]
	v_readlane_b32 s8, v108, 42
	s_nop 1
	v_pk_fma_f32 v[44:45], v[48:49], s[8:9], v[44:45] op_sel_hi:[1,0,1]
	v_pk_fma_f32 v[42:43], v[46:47], s[8:9], v[42:43] op_sel_hi:[1,0,1]
	v_readlane_b32 s8, v109, 42
	s_nop 1
	v_pk_fma_f32 v[52:53], v[48:49], s[8:9], v[52:53] op_sel_hi:[1,0,1]
	v_pk_fma_f32 v[50:51], v[46:47], s[8:9], v[50:51] op_sel_hi:[1,0,1]
	v_readlane_b32 s8, v110, 42
	s_nop 1
	v_pk_fma_f32 v[56:57], v[48:49], s[8:9], v[56:57] op_sel_hi:[1,0,1]
	v_pk_fma_f32 v[54:55], v[46:47], s[8:9], v[54:55] op_sel_hi:[1,0,1]
	v_readlane_b32 s8, v111, 42
	s_nop 0
	v_pk_fma_f32 v[48:49], v[48:49], s[8:9], v[60:61] op_sel_hi:[1,0,1]
	v_pk_fma_f32 v[46:47], v[46:47], s[8:9], v[58:59] op_sel_hi:[1,0,1]
	v_readlane_b32 s8, v1, 43
	s_waitcnt vmcnt(20)
	s_nop 0
	v_pk_fma_f32 v[24:25], v[20:21], s[8:9], v[24:25] op_sel_hi:[1,0,1]
	v_pk_fma_f32 v[22:23], v[18:19], s[8:9], v[22:23] op_sel_hi:[1,0,1]
	v_readlane_b32 s8, v104, 43
	s_nop 1
	v_pk_fma_f32 v[28:29], v[20:21], s[8:9], v[28:29] op_sel_hi:[1,0,1]
	v_pk_fma_f32 v[26:27], v[18:19], s[8:9], v[26:27] op_sel_hi:[1,0,1]
	v_readlane_b32 s8, v105, 43
	s_nop 1
	v_pk_fma_f32 v[32:33], v[20:21], s[8:9], v[32:33] op_sel_hi:[1,0,1]
	v_pk_fma_f32 v[30:31], v[18:19], s[8:9], v[30:31] op_sel_hi:[1,0,1]
	v_readlane_b32 s8, v106, 43
	s_nop 1
	v_pk_fma_f32 v[36:37], v[20:21], s[8:9], v[36:37] op_sel_hi:[1,0,1]
	v_pk_fma_f32 v[34:35], v[18:19], s[8:9], v[34:35] op_sel_hi:[1,0,1]
	v_readlane_b32 s8, v107, 43
	s_nop 1
	v_pk_fma_f32 v[40:41], v[20:21], s[8:9], v[40:41] op_sel_hi:[1,0,1]
	v_pk_fma_f32 v[38:39], v[18:19], s[8:9], v[38:39] op_sel_hi:[1,0,1]
	v_readlane_b32 s8, v108, 43
	s_nop 1
	v_pk_fma_f32 v[44:45], v[20:21], s[8:9], v[44:45] op_sel_hi:[1,0,1]
	v_pk_fma_f32 v[42:43], v[18:19], s[8:9], v[42:43] op_sel_hi:[1,0,1]
	v_readlane_b32 s8, v109, 43
	s_nop 1
	v_pk_fma_f32 v[52:53], v[20:21], s[8:9], v[52:53] op_sel_hi:[1,0,1]
	v_pk_fma_f32 v[50:51], v[18:19], s[8:9], v[50:51] op_sel_hi:[1,0,1]
	v_readlane_b32 s8, v110, 43
	s_nop 1
	v_pk_fma_f32 v[56:57], v[20:21], s[8:9], v[56:57] op_sel_hi:[1,0,1]
	v_pk_fma_f32 v[54:55], v[18:19], s[8:9], v[54:55] op_sel_hi:[1,0,1]
	v_readlane_b32 s8, v111, 43
	s_nop 0
	v_pk_fma_f32 v[20:21], v[20:21], s[8:9], v[48:49] op_sel_hi:[1,0,1]
	v_pk_fma_f32 v[18:19], v[18:19], s[8:9], v[46:47] op_sel_hi:[1,0,1]
	v_readlane_b32 s8, v1, 44
	s_waitcnt vmcnt(19)
	s_nop 0
	v_pk_fma_f32 v[24:25], v[16:17], s[8:9], v[24:25] op_sel_hi:[1,0,1]
	v_pk_fma_f32 v[22:23], v[14:15], s[8:9], v[22:23] op_sel_hi:[1,0,1]
	v_readlane_b32 s8, v104, 44
	s_nop 1
	v_pk_fma_f32 v[28:29], v[16:17], s[8:9], v[28:29] op_sel_hi:[1,0,1]
	v_pk_fma_f32 v[26:27], v[14:15], s[8:9], v[26:27] op_sel_hi:[1,0,1]
	v_readlane_b32 s8, v105, 44
	s_nop 1
	v_pk_fma_f32 v[32:33], v[16:17], s[8:9], v[32:33] op_sel_hi:[1,0,1]
	v_pk_fma_f32 v[30:31], v[14:15], s[8:9], v[30:31] op_sel_hi:[1,0,1]
	v_readlane_b32 s8, v106, 44
	s_nop 1
	v_pk_fma_f32 v[36:37], v[16:17], s[8:9], v[36:37] op_sel_hi:[1,0,1]
	v_pk_fma_f32 v[34:35], v[14:15], s[8:9], v[34:35] op_sel_hi:[1,0,1]
	v_readlane_b32 s8, v107, 44
	s_nop 1
	v_pk_fma_f32 v[40:41], v[16:17], s[8:9], v[40:41] op_sel_hi:[1,0,1]
	v_pk_fma_f32 v[38:39], v[14:15], s[8:9], v[38:39] op_sel_hi:[1,0,1]
	v_readlane_b32 s8, v108, 44
	s_nop 1
	v_pk_fma_f32 v[44:45], v[16:17], s[8:9], v[44:45] op_sel_hi:[1,0,1]
	v_pk_fma_f32 v[42:43], v[14:15], s[8:9], v[42:43] op_sel_hi:[1,0,1]
	v_readlane_b32 s8, v109, 44
	s_nop 1
	v_pk_fma_f32 v[46:47], v[16:17], s[8:9], v[52:53] op_sel_hi:[1,0,1]
	v_pk_fma_f32 v[48:49], v[14:15], s[8:9], v[50:51] op_sel_hi:[1,0,1]
	v_readlane_b32 s8, v110, 44
	s_nop 1
	v_pk_fma_f32 v[50:51], v[16:17], s[8:9], v[56:57] op_sel_hi:[1,0,1]
	v_pk_fma_f32 v[52:53], v[14:15], s[8:9], v[54:55] op_sel_hi:[1,0,1]
	v_readlane_b32 s8, v111, 44
	s_nop 0
	v_pk_fma_f32 v[16:17], v[16:17], s[8:9], v[20:21] op_sel_hi:[1,0,1]
	v_pk_fma_f32 v[14:15], v[14:15], s[8:9], v[18:19] op_sel_hi:[1,0,1]
	v_readlane_b32 s8, v1, 45
	s_waitcnt vmcnt(18)
	s_nop 0
	v_pk_fma_f32 v[18:19], v[12:13], s[8:9], v[24:25] op_sel_hi:[1,0,1]
	v_pk_fma_f32 v[20:21], v[10:11], s[8:9], v[22:23] op_sel_hi:[1,0,1]
	v_readlane_b32 s8, v104, 45
	s_nop 1
	v_pk_fma_f32 v[22:23], v[12:13], s[8:9], v[28:29] op_sel_hi:[1,0,1]
	v_pk_fma_f32 v[24:25], v[10:11], s[8:9], v[26:27] op_sel_hi:[1,0,1]
	v_readlane_b32 s8, v105, 45
	s_nop 1
	v_pk_fma_f32 v[26:27], v[12:13], s[8:9], v[32:33] op_sel_hi:[1,0,1]
	v_pk_fma_f32 v[28:29], v[10:11], s[8:9], v[30:31] op_sel_hi:[1,0,1]
	v_readlane_b32 s8, v106, 45
	s_nop 1
	v_pk_fma_f32 v[30:31], v[12:13], s[8:9], v[36:37] op_sel_hi:[1,0,1]
	v_pk_fma_f32 v[32:33], v[10:11], s[8:9], v[34:35] op_sel_hi:[1,0,1]
	v_readlane_b32 s8, v107, 45
	s_nop 1
	v_pk_fma_f32 v[34:35], v[12:13], s[8:9], v[40:41] op_sel_hi:[1,0,1]
	v_pk_fma_f32 v[36:37], v[10:11], s[8:9], v[38:39] op_sel_hi:[1,0,1]
	v_readlane_b32 s8, v108, 45
	s_nop 1
	v_pk_fma_f32 v[38:39], v[12:13], s[8:9], v[44:45] op_sel_hi:[1,0,1]
	v_pk_fma_f32 v[40:41], v[10:11], s[8:9], v[42:43] op_sel_hi:[1,0,1]
	v_readlane_b32 s8, v109, 45
	s_nop 1
	v_pk_fma_f32 v[42:43], v[12:13], s[8:9], v[46:47] op_sel_hi:[1,0,1]
	v_pk_fma_f32 v[44:45], v[10:11], s[8:9], v[48:49] op_sel_hi:[1,0,1]
	v_readlane_b32 s8, v110, 45
	s_nop 1
	v_pk_fma_f32 v[46:47], v[12:13], s[8:9], v[50:51] op_sel_hi:[1,0,1]
	v_pk_fma_f32 v[48:49], v[10:11], s[8:9], v[52:53] op_sel_hi:[1,0,1]
	v_readlane_b32 s8, v111, 45
	s_nop 0
	v_pk_fma_f32 v[12:13], v[12:13], s[8:9], v[16:17] op_sel_hi:[1,0,1]
	v_pk_fma_f32 v[10:11], v[10:11], s[8:9], v[14:15] op_sel_hi:[1,0,1]
	v_readlane_b32 s8, v1, 46
	s_waitcnt vmcnt(17)
	s_nop 0
	v_pk_fma_f32 v[14:15], v[8:9], s[8:9], v[18:19] op_sel_hi:[1,0,1]
	v_pk_fma_f32 v[16:17], v[6:7], s[8:9], v[20:21] op_sel_hi:[1,0,1]
	v_readlane_b32 s8, v104, 46
	s_nop 1
	v_pk_fma_f32 v[18:19], v[8:9], s[8:9], v[22:23] op_sel_hi:[1,0,1]
	v_pk_fma_f32 v[20:21], v[6:7], s[8:9], v[24:25] op_sel_hi:[1,0,1]
	v_readlane_b32 s8, v105, 46
	s_nop 1
	v_pk_fma_f32 v[50:51], v[8:9], s[8:9], v[26:27] op_sel_hi:[1,0,1]
	v_pk_fma_f32 v[52:53], v[6:7], s[8:9], v[28:29] op_sel_hi:[1,0,1]
	v_readlane_b32 s8, v106, 46
	s_nop 1
	v_pk_fma_f32 v[54:55], v[8:9], s[8:9], v[30:31] op_sel_hi:[1,0,1]
	v_pk_fma_f32 v[56:57], v[6:7], s[8:9], v[32:33] op_sel_hi:[1,0,1]
	v_readlane_b32 s8, v107, 46
	s_nop 1
	v_pk_fma_f32 v[58:59], v[8:9], s[8:9], v[34:35] op_sel_hi:[1,0,1]
	v_pk_fma_f32 v[60:61], v[6:7], s[8:9], v[36:37] op_sel_hi:[1,0,1]
	v_readlane_b32 s8, v108, 46
	s_nop 1
	v_pk_fma_f32 v[62:63], v[8:9], s[8:9], v[38:39] op_sel_hi:[1,0,1]
	v_pk_fma_f32 v[64:65], v[6:7], s[8:9], v[40:41] op_sel_hi:[1,0,1]
	v_readlane_b32 s8, v109, 46
	s_nop 1
	v_pk_fma_f32 v[66:67], v[8:9], s[8:9], v[42:43] op_sel_hi:[1,0,1]
	v_pk_fma_f32 v[68:69], v[6:7], s[8:9], v[44:45] op_sel_hi:[1,0,1]
	v_readlane_b32 s8, v110, 46
	s_nop 1
	v_pk_fma_f32 v[46:47], v[8:9], s[8:9], v[46:47] op_sel_hi:[1,0,1]
	v_pk_fma_f32 v[48:49], v[6:7], s[8:9], v[48:49] op_sel_hi:[1,0,1]
	v_readlane_b32 s8, v111, 46
	s_nop 0
	v_pk_fma_f32 v[8:9], v[8:9], s[8:9], v[12:13] op_sel_hi:[1,0,1]
	v_pk_fma_f32 v[6:7], v[6:7], s[8:9], v[10:11] op_sel_hi:[1,0,1]
	v_readlane_b32 s8, v1, 47
	s_waitcnt vmcnt(16)
	s_nop 0
	v_pk_fma_f32 v[24:25], v[4:5], s[8:9], v[14:15] op_sel_hi:[1,0,1]
	v_pk_fma_f32 v[22:23], v[2:3], s[8:9], v[16:17] op_sel_hi:[1,0,1]
	v_readlane_b32 s8, v104, 47
	s_nop 1
	v_pk_fma_f32 v[28:29], v[4:5], s[8:9], v[18:19] op_sel_hi:[1,0,1]
	v_pk_fma_f32 v[26:27], v[2:3], s[8:9], v[20:21] op_sel_hi:[1,0,1]
	v_readlane_b32 s8, v105, 47
	s_nop 1
	v_pk_fma_f32 v[32:33], v[4:5], s[8:9], v[50:51] op_sel_hi:[1,0,1]
	v_pk_fma_f32 v[30:31], v[2:3], s[8:9], v[52:53] op_sel_hi:[1,0,1]
	v_readlane_b32 s8, v106, 47
	s_nop 1
	v_pk_fma_f32 v[36:37], v[4:5], s[8:9], v[54:55] op_sel_hi:[1,0,1]
	v_pk_fma_f32 v[34:35], v[2:3], s[8:9], v[56:57] op_sel_hi:[1,0,1]
	v_readlane_b32 s8, v107, 47
	s_nop 1
	v_pk_fma_f32 v[40:41], v[4:5], s[8:9], v[58:59] op_sel_hi:[1,0,1]
	v_pk_fma_f32 v[38:39], v[2:3], s[8:9], v[60:61] op_sel_hi:[1,0,1]
	v_readlane_b32 s8, v108, 47
	s_nop 1
	v_pk_fma_f32 v[44:45], v[4:5], s[8:9], v[62:63] op_sel_hi:[1,0,1]
	v_pk_fma_f32 v[42:43], v[2:3], s[8:9], v[64:65] op_sel_hi:[1,0,1]
	v_readlane_b32 s8, v109, 47
	s_nop 1
	v_pk_fma_f32 v[52:53], v[4:5], s[8:9], v[66:67] op_sel_hi:[1,0,1]
	v_pk_fma_f32 v[50:51], v[2:3], s[8:9], v[68:69] op_sel_hi:[1,0,1]
	v_readlane_b32 s8, v110, 47
	s_nop 1
	v_pk_fma_f32 v[56:57], v[4:5], s[8:9], v[46:47] op_sel_hi:[1,0,1]
	v_pk_fma_f32 v[54:55], v[2:3], s[8:9], v[48:49] op_sel_hi:[1,0,1]
	v_readlane_b32 s8, v111, 47
	v_pk_fma_f32 v[60:61], v[4:5], s[8:9], v[8:9] op_sel_hi:[1,0,1]
	v_pk_fma_f32 v[58:59], v[2:3], s[8:9], v[6:7] op_sel_hi:[1,0,1]
	v_readlane_b32 s8, v1, 48
	s_waitcnt vmcnt(15)
	v_pk_fma_f32 v[24:25], v[122:123], s[8:9], v[24:25] op_sel_hi:[1,0,1]
	v_pk_fma_f32 v[22:23], v[120:121], s[8:9], v[22:23] op_sel_hi:[1,0,1]
	v_readlane_b32 s8, v104, 48
	s_nop 1
	v_pk_fma_f32 v[28:29], v[122:123], s[8:9], v[28:29] op_sel_hi:[1,0,1]
	v_pk_fma_f32 v[26:27], v[120:121], s[8:9], v[26:27] op_sel_hi:[1,0,1]
	v_readlane_b32 s8, v105, 48
	s_nop 1
	v_pk_fma_f32 v[32:33], v[122:123], s[8:9], v[32:33] op_sel_hi:[1,0,1]
	v_pk_fma_f32 v[30:31], v[120:121], s[8:9], v[30:31] op_sel_hi:[1,0,1]
	v_readlane_b32 s8, v106, 48
	s_nop 1
	v_pk_fma_f32 v[36:37], v[122:123], s[8:9], v[36:37] op_sel_hi:[1,0,1]
	v_pk_fma_f32 v[34:35], v[120:121], s[8:9], v[34:35] op_sel_hi:[1,0,1]
	v_readlane_b32 s8, v107, 48
	s_nop 1
	v_pk_fma_f32 v[40:41], v[122:123], s[8:9], v[40:41] op_sel_hi:[1,0,1]
	v_pk_fma_f32 v[38:39], v[120:121], s[8:9], v[38:39] op_sel_hi:[1,0,1]
	v_readlane_b32 s8, v108, 48
	s_nop 1
	v_pk_fma_f32 v[44:45], v[122:123], s[8:9], v[44:45] op_sel_hi:[1,0,1]
	v_pk_fma_f32 v[42:43], v[120:121], s[8:9], v[42:43] op_sel_hi:[1,0,1]
	v_readlane_b32 s8, v109, 48
	s_nop 1
	v_pk_fma_f32 v[52:53], v[122:123], s[8:9], v[52:53] op_sel_hi:[1,0,1]
	v_pk_fma_f32 v[50:51], v[120:121], s[8:9], v[50:51] op_sel_hi:[1,0,1]
	v_readlane_b32 s8, v110, 48
	s_nop 1
	v_pk_fma_f32 v[56:57], v[122:123], s[8:9], v[56:57] op_sel_hi:[1,0,1]
	v_pk_fma_f32 v[54:55], v[120:121], s[8:9], v[54:55] op_sel_hi:[1,0,1]
	v_readlane_b32 s8, v111, 48
	s_nop 1
	v_pk_fma_f32 v[60:61], v[122:123], s[8:9], v[60:61] op_sel_hi:[1,0,1]
	v_pk_fma_f32 v[58:59], v[120:121], s[8:9], v[58:59] op_sel_hi:[1,0,1]
	v_readlane_b32 s8, v1, 49
	s_waitcnt vmcnt(14)
	s_nop 0
	v_pk_fma_f32 v[24:25], v[126:127], s[8:9], v[24:25] op_sel_hi:[1,0,1]
	v_pk_fma_f32 v[22:23], v[124:125], s[8:9], v[22:23] op_sel_hi:[1,0,1]
	v_readlane_b32 s8, v104, 49
	s_nop 1
	v_pk_fma_f32 v[28:29], v[126:127], s[8:9], v[28:29] op_sel_hi:[1,0,1]
	v_pk_fma_f32 v[26:27], v[124:125], s[8:9], v[26:27] op_sel_hi:[1,0,1]
	v_readlane_b32 s8, v105, 49
	s_nop 1
	v_pk_fma_f32 v[32:33], v[126:127], s[8:9], v[32:33] op_sel_hi:[1,0,1]
	v_pk_fma_f32 v[30:31], v[124:125], s[8:9], v[30:31] op_sel_hi:[1,0,1]
	v_readlane_b32 s8, v106, 49
	s_nop 1
	v_pk_fma_f32 v[36:37], v[126:127], s[8:9], v[36:37] op_sel_hi:[1,0,1]
	v_pk_fma_f32 v[34:35], v[124:125], s[8:9], v[34:35] op_sel_hi:[1,0,1]
	v_readlane_b32 s8, v107, 49
	s_nop 1
	v_pk_fma_f32 v[40:41], v[126:127], s[8:9], v[40:41] op_sel_hi:[1,0,1]
	v_pk_fma_f32 v[38:39], v[124:125], s[8:9], v[38:39] op_sel_hi:[1,0,1]
	v_readlane_b32 s8, v108, 49
	s_nop 1
	v_pk_fma_f32 v[44:45], v[126:127], s[8:9], v[44:45] op_sel_hi:[1,0,1]
	v_pk_fma_f32 v[42:43], v[124:125], s[8:9], v[42:43] op_sel_hi:[1,0,1]
	v_readlane_b32 s8, v109, 49
	s_nop 1
	v_pk_fma_f32 v[52:53], v[126:127], s[8:9], v[52:53] op_sel_hi:[1,0,1]
	v_pk_fma_f32 v[50:51], v[124:125], s[8:9], v[50:51] op_sel_hi:[1,0,1]
	v_readlane_b32 s8, v110, 49
	s_nop 1
	v_pk_fma_f32 v[56:57], v[126:127], s[8:9], v[56:57] op_sel_hi:[1,0,1]
	v_pk_fma_f32 v[54:55], v[124:125], s[8:9], v[54:55] op_sel_hi:[1,0,1]
	v_readlane_b32 s8, v111, 49
	s_nop 0
	v_pk_fma_f32 v[60:61], v[126:127], s[8:9], v[60:61] op_sel_hi:[1,0,1]
	v_pk_fma_f32 v[58:59], v[124:125], s[8:9], v[58:59] op_sel_hi:[1,0,1]
	v_readlane_b32 s8, v1, 50
	s_waitcnt vmcnt(13)
	s_nop 0
	v_pk_fma_f32 v[24:25], v[130:131], s[8:9], v[24:25] op_sel_hi:[1,0,1]
	v_pk_fma_f32 v[22:23], v[128:129], s[8:9], v[22:23] op_sel_hi:[1,0,1]
	v_readlane_b32 s8, v104, 50
	s_nop 1
	v_pk_fma_f32 v[28:29], v[130:131], s[8:9], v[28:29] op_sel_hi:[1,0,1]
	v_pk_fma_f32 v[26:27], v[128:129], s[8:9], v[26:27] op_sel_hi:[1,0,1]
	v_readlane_b32 s8, v105, 50
	s_nop 1
	v_pk_fma_f32 v[32:33], v[130:131], s[8:9], v[32:33] op_sel_hi:[1,0,1]
	v_pk_fma_f32 v[30:31], v[128:129], s[8:9], v[30:31] op_sel_hi:[1,0,1]
	v_readlane_b32 s8, v106, 50
	s_nop 1
	v_pk_fma_f32 v[36:37], v[130:131], s[8:9], v[36:37] op_sel_hi:[1,0,1]
	v_pk_fma_f32 v[34:35], v[128:129], s[8:9], v[34:35] op_sel_hi:[1,0,1]
	v_readlane_b32 s8, v107, 50
	s_nop 1
	v_pk_fma_f32 v[40:41], v[130:131], s[8:9], v[40:41] op_sel_hi:[1,0,1]
	v_pk_fma_f32 v[38:39], v[128:129], s[8:9], v[38:39] op_sel_hi:[1,0,1]
	v_readlane_b32 s8, v108, 50
	s_nop 1
	v_pk_fma_f32 v[44:45], v[130:131], s[8:9], v[44:45] op_sel_hi:[1,0,1]
	v_pk_fma_f32 v[42:43], v[128:129], s[8:9], v[42:43] op_sel_hi:[1,0,1]
	v_readlane_b32 s8, v109, 50
	s_nop 1
	v_pk_fma_f32 v[52:53], v[130:131], s[8:9], v[52:53] op_sel_hi:[1,0,1]
	v_pk_fma_f32 v[50:51], v[128:129], s[8:9], v[50:51] op_sel_hi:[1,0,1]
	v_readlane_b32 s8, v110, 50
	s_nop 1
	v_pk_fma_f32 v[56:57], v[130:131], s[8:9], v[56:57] op_sel_hi:[1,0,1]
	v_pk_fma_f32 v[54:55], v[128:129], s[8:9], v[54:55] op_sel_hi:[1,0,1]
	v_readlane_b32 s8, v111, 50
	s_nop 0
	v_pk_fma_f32 v[60:61], v[130:131], s[8:9], v[60:61] op_sel_hi:[1,0,1]
	v_pk_fma_f32 v[58:59], v[128:129], s[8:9], v[58:59] op_sel_hi:[1,0,1]
	v_readlane_b32 s8, v1, 51
	s_waitcnt vmcnt(12)
	s_nop 0
	v_pk_fma_f32 v[24:25], v[134:135], s[8:9], v[24:25] op_sel_hi:[1,0,1]
	v_pk_fma_f32 v[22:23], v[132:133], s[8:9], v[22:23] op_sel_hi:[1,0,1]
	v_readlane_b32 s8, v104, 51
	s_nop 1
	v_pk_fma_f32 v[28:29], v[134:135], s[8:9], v[28:29] op_sel_hi:[1,0,1]
	v_pk_fma_f32 v[26:27], v[132:133], s[8:9], v[26:27] op_sel_hi:[1,0,1]
	v_readlane_b32 s8, v105, 51
	s_nop 1
	v_pk_fma_f32 v[32:33], v[134:135], s[8:9], v[32:33] op_sel_hi:[1,0,1]
	v_pk_fma_f32 v[30:31], v[132:133], s[8:9], v[30:31] op_sel_hi:[1,0,1]
	v_readlane_b32 s8, v106, 51
	s_nop 1
	v_pk_fma_f32 v[36:37], v[134:135], s[8:9], v[36:37] op_sel_hi:[1,0,1]
	v_pk_fma_f32 v[34:35], v[132:133], s[8:9], v[34:35] op_sel_hi:[1,0,1]
	v_readlane_b32 s8, v107, 51
	s_nop 1
	v_pk_fma_f32 v[40:41], v[134:135], s[8:9], v[40:41] op_sel_hi:[1,0,1]
	v_pk_fma_f32 v[38:39], v[132:133], s[8:9], v[38:39] op_sel_hi:[1,0,1]
	v_readlane_b32 s8, v108, 51
	s_nop 1
	v_pk_fma_f32 v[44:45], v[134:135], s[8:9], v[44:45] op_sel_hi:[1,0,1]
	v_pk_fma_f32 v[42:43], v[132:133], s[8:9], v[42:43] op_sel_hi:[1,0,1]
	v_readlane_b32 s8, v109, 51
	s_nop 1
	v_pk_fma_f32 v[52:53], v[134:135], s[8:9], v[52:53] op_sel_hi:[1,0,1]
	v_pk_fma_f32 v[50:51], v[132:133], s[8:9], v[50:51] op_sel_hi:[1,0,1]
	v_readlane_b32 s8, v110, 51
	s_nop 1
	v_pk_fma_f32 v[56:57], v[134:135], s[8:9], v[56:57] op_sel_hi:[1,0,1]
	v_pk_fma_f32 v[54:55], v[132:133], s[8:9], v[54:55] op_sel_hi:[1,0,1]
	v_readlane_b32 s8, v111, 51
	s_nop 0
	v_pk_fma_f32 v[60:61], v[134:135], s[8:9], v[60:61] op_sel_hi:[1,0,1]
	v_pk_fma_f32 v[58:59], v[132:133], s[8:9], v[58:59] op_sel_hi:[1,0,1]
	v_readlane_b32 s8, v1, 52
	s_waitcnt vmcnt(11)
	s_nop 0
	v_pk_fma_f32 v[24:25], v[138:139], s[8:9], v[24:25] op_sel_hi:[1,0,1]
	v_pk_fma_f32 v[22:23], v[136:137], s[8:9], v[22:23] op_sel_hi:[1,0,1]
	v_readlane_b32 s8, v104, 52
	s_nop 1
	v_pk_fma_f32 v[28:29], v[138:139], s[8:9], v[28:29] op_sel_hi:[1,0,1]
	v_pk_fma_f32 v[26:27], v[136:137], s[8:9], v[26:27] op_sel_hi:[1,0,1]
	v_readlane_b32 s8, v105, 52
	s_nop 1
	v_pk_fma_f32 v[32:33], v[138:139], s[8:9], v[32:33] op_sel_hi:[1,0,1]
	v_pk_fma_f32 v[30:31], v[136:137], s[8:9], v[30:31] op_sel_hi:[1,0,1]
	v_readlane_b32 s8, v106, 52
	s_nop 1
	v_pk_fma_f32 v[36:37], v[138:139], s[8:9], v[36:37] op_sel_hi:[1,0,1]
	v_pk_fma_f32 v[34:35], v[136:137], s[8:9], v[34:35] op_sel_hi:[1,0,1]
	v_readlane_b32 s8, v107, 52
	s_nop 1
	v_pk_fma_f32 v[40:41], v[138:139], s[8:9], v[40:41] op_sel_hi:[1,0,1]
	v_pk_fma_f32 v[38:39], v[136:137], s[8:9], v[38:39] op_sel_hi:[1,0,1]
	v_readlane_b32 s8, v108, 52
	s_nop 1
	v_pk_fma_f32 v[44:45], v[138:139], s[8:9], v[44:45] op_sel_hi:[1,0,1]
	v_pk_fma_f32 v[42:43], v[136:137], s[8:9], v[42:43] op_sel_hi:[1,0,1]
	v_readlane_b32 s8, v109, 52
	s_nop 1
	v_pk_fma_f32 v[52:53], v[138:139], s[8:9], v[52:53] op_sel_hi:[1,0,1]
	v_pk_fma_f32 v[50:51], v[136:137], s[8:9], v[50:51] op_sel_hi:[1,0,1]
	v_readlane_b32 s8, v110, 52
	s_nop 1
	v_pk_fma_f32 v[56:57], v[138:139], s[8:9], v[56:57] op_sel_hi:[1,0,1]
	v_pk_fma_f32 v[54:55], v[136:137], s[8:9], v[54:55] op_sel_hi:[1,0,1]
	v_readlane_b32 s8, v111, 52
	s_nop 0
	v_pk_fma_f32 v[60:61], v[138:139], s[8:9], v[60:61] op_sel_hi:[1,0,1]
	v_pk_fma_f32 v[58:59], v[136:137], s[8:9], v[58:59] op_sel_hi:[1,0,1]
	v_readlane_b32 s8, v1, 53
	s_waitcnt vmcnt(10)
	s_nop 0
	v_pk_fma_f32 v[24:25], v[142:143], s[8:9], v[24:25] op_sel_hi:[1,0,1]
	v_pk_fma_f32 v[22:23], v[140:141], s[8:9], v[22:23] op_sel_hi:[1,0,1]
	v_readlane_b32 s8, v104, 53
	s_nop 1
	v_pk_fma_f32 v[28:29], v[142:143], s[8:9], v[28:29] op_sel_hi:[1,0,1]
	v_pk_fma_f32 v[26:27], v[140:141], s[8:9], v[26:27] op_sel_hi:[1,0,1]
	v_readlane_b32 s8, v105, 53
	s_nop 1
	v_pk_fma_f32 v[32:33], v[142:143], s[8:9], v[32:33] op_sel_hi:[1,0,1]
	v_pk_fma_f32 v[30:31], v[140:141], s[8:9], v[30:31] op_sel_hi:[1,0,1]
	v_readlane_b32 s8, v106, 53
	s_nop 1
	v_pk_fma_f32 v[36:37], v[142:143], s[8:9], v[36:37] op_sel_hi:[1,0,1]
	v_pk_fma_f32 v[34:35], v[140:141], s[8:9], v[34:35] op_sel_hi:[1,0,1]
	v_readlane_b32 s8, v107, 53
	s_nop 1
	v_pk_fma_f32 v[40:41], v[142:143], s[8:9], v[40:41] op_sel_hi:[1,0,1]
	v_pk_fma_f32 v[38:39], v[140:141], s[8:9], v[38:39] op_sel_hi:[1,0,1]
	v_readlane_b32 s8, v108, 53
	s_nop 1
	v_pk_fma_f32 v[44:45], v[142:143], s[8:9], v[44:45] op_sel_hi:[1,0,1]
	v_pk_fma_f32 v[42:43], v[140:141], s[8:9], v[42:43] op_sel_hi:[1,0,1]
	v_readlane_b32 s8, v109, 53
	s_nop 1
	v_pk_fma_f32 v[52:53], v[142:143], s[8:9], v[52:53] op_sel_hi:[1,0,1]
	v_pk_fma_f32 v[50:51], v[140:141], s[8:9], v[50:51] op_sel_hi:[1,0,1]
	v_readlane_b32 s8, v110, 53
	s_nop 1
	v_pk_fma_f32 v[56:57], v[142:143], s[8:9], v[56:57] op_sel_hi:[1,0,1]
	v_pk_fma_f32 v[54:55], v[140:141], s[8:9], v[54:55] op_sel_hi:[1,0,1]
	v_readlane_b32 s8, v111, 53
	s_nop 0
	v_pk_fma_f32 v[60:61], v[142:143], s[8:9], v[60:61] op_sel_hi:[1,0,1]
	v_pk_fma_f32 v[58:59], v[140:141], s[8:9], v[58:59] op_sel_hi:[1,0,1]
	v_readlane_b32 s8, v1, 54
	s_waitcnt vmcnt(9)
	s_nop 0
	v_pk_fma_f32 v[24:25], v[146:147], s[8:9], v[24:25] op_sel_hi:[1,0,1]
	v_pk_fma_f32 v[22:23], v[144:145], s[8:9], v[22:23] op_sel_hi:[1,0,1]
	v_readlane_b32 s8, v104, 54
	s_nop 1
	v_pk_fma_f32 v[28:29], v[146:147], s[8:9], v[28:29] op_sel_hi:[1,0,1]
	v_pk_fma_f32 v[26:27], v[144:145], s[8:9], v[26:27] op_sel_hi:[1,0,1]
	v_readlane_b32 s8, v105, 54
	s_nop 1
	v_pk_fma_f32 v[32:33], v[146:147], s[8:9], v[32:33] op_sel_hi:[1,0,1]
	v_pk_fma_f32 v[30:31], v[144:145], s[8:9], v[30:31] op_sel_hi:[1,0,1]
	v_readlane_b32 s8, v106, 54
	s_nop 1
	v_pk_fma_f32 v[36:37], v[146:147], s[8:9], v[36:37] op_sel_hi:[1,0,1]
	v_pk_fma_f32 v[34:35], v[144:145], s[8:9], v[34:35] op_sel_hi:[1,0,1]
	v_readlane_b32 s8, v107, 54
	s_nop 1
	v_pk_fma_f32 v[40:41], v[146:147], s[8:9], v[40:41] op_sel_hi:[1,0,1]
	v_pk_fma_f32 v[38:39], v[144:145], s[8:9], v[38:39] op_sel_hi:[1,0,1]
	v_readlane_b32 s8, v108, 54
	s_nop 1
	v_pk_fma_f32 v[44:45], v[146:147], s[8:9], v[44:45] op_sel_hi:[1,0,1]
	v_pk_fma_f32 v[42:43], v[144:145], s[8:9], v[42:43] op_sel_hi:[1,0,1]
	v_readlane_b32 s8, v109, 54
	s_nop 1
	v_pk_fma_f32 v[52:53], v[146:147], s[8:9], v[52:53] op_sel_hi:[1,0,1]
	v_pk_fma_f32 v[50:51], v[144:145], s[8:9], v[50:51] op_sel_hi:[1,0,1]
	v_readlane_b32 s8, v110, 54
	s_nop 1
	v_pk_fma_f32 v[56:57], v[146:147], s[8:9], v[56:57] op_sel_hi:[1,0,1]
	v_pk_fma_f32 v[54:55], v[144:145], s[8:9], v[54:55] op_sel_hi:[1,0,1]
	v_readlane_b32 s8, v111, 54
	s_nop 0
	v_pk_fma_f32 v[60:61], v[146:147], s[8:9], v[60:61] op_sel_hi:[1,0,1]
	v_pk_fma_f32 v[58:59], v[144:145], s[8:9], v[58:59] op_sel_hi:[1,0,1]
	v_readlane_b32 s8, v1, 55
	s_waitcnt vmcnt(8)
	s_nop 0
	v_pk_fma_f32 v[24:25], v[150:151], s[8:9], v[24:25] op_sel_hi:[1,0,1]
	v_pk_fma_f32 v[22:23], v[148:149], s[8:9], v[22:23] op_sel_hi:[1,0,1]
	v_readlane_b32 s8, v104, 55
	s_nop 1
	v_pk_fma_f32 v[28:29], v[150:151], s[8:9], v[28:29] op_sel_hi:[1,0,1]
	v_pk_fma_f32 v[26:27], v[148:149], s[8:9], v[26:27] op_sel_hi:[1,0,1]
	v_readlane_b32 s8, v105, 55
	s_nop 1
	v_pk_fma_f32 v[32:33], v[150:151], s[8:9], v[32:33] op_sel_hi:[1,0,1]
	v_pk_fma_f32 v[30:31], v[148:149], s[8:9], v[30:31] op_sel_hi:[1,0,1]
	v_readlane_b32 s8, v106, 55
	s_nop 1
	v_pk_fma_f32 v[36:37], v[150:151], s[8:9], v[36:37] op_sel_hi:[1,0,1]
	v_pk_fma_f32 v[34:35], v[148:149], s[8:9], v[34:35] op_sel_hi:[1,0,1]
	v_readlane_b32 s8, v107, 55
	s_nop 1
	v_pk_fma_f32 v[40:41], v[150:151], s[8:9], v[40:41] op_sel_hi:[1,0,1]
	v_pk_fma_f32 v[38:39], v[148:149], s[8:9], v[38:39] op_sel_hi:[1,0,1]
	v_readlane_b32 s8, v108, 55
	s_nop 1
	v_pk_fma_f32 v[44:45], v[150:151], s[8:9], v[44:45] op_sel_hi:[1,0,1]
	v_pk_fma_f32 v[42:43], v[148:149], s[8:9], v[42:43] op_sel_hi:[1,0,1]
	v_readlane_b32 s8, v109, 55
	s_nop 1
	v_pk_fma_f32 v[52:53], v[150:151], s[8:9], v[52:53] op_sel_hi:[1,0,1]
	v_pk_fma_f32 v[50:51], v[148:149], s[8:9], v[50:51] op_sel_hi:[1,0,1]
	v_readlane_b32 s8, v110, 55
	s_nop 1
	v_pk_fma_f32 v[56:57], v[150:151], s[8:9], v[56:57] op_sel_hi:[1,0,1]
	v_pk_fma_f32 v[54:55], v[148:149], s[8:9], v[54:55] op_sel_hi:[1,0,1]
	v_readlane_b32 s8, v111, 55
	s_nop 0
	v_pk_fma_f32 v[60:61], v[150:151], s[8:9], v[60:61] op_sel_hi:[1,0,1]
	v_pk_fma_f32 v[58:59], v[148:149], s[8:9], v[58:59] op_sel_hi:[1,0,1]
	v_readlane_b32 s8, v1, 56
	s_waitcnt vmcnt(7)
	s_nop 0
	v_pk_fma_f32 v[24:25], v[154:155], s[8:9], v[24:25] op_sel_hi:[1,0,1]
	v_pk_fma_f32 v[22:23], v[152:153], s[8:9], v[22:23] op_sel_hi:[1,0,1]
	v_readlane_b32 s8, v104, 56
	s_nop 1
	v_pk_fma_f32 v[28:29], v[154:155], s[8:9], v[28:29] op_sel_hi:[1,0,1]
	v_pk_fma_f32 v[26:27], v[152:153], s[8:9], v[26:27] op_sel_hi:[1,0,1]
	v_readlane_b32 s8, v105, 56
	s_nop 1
	v_pk_fma_f32 v[32:33], v[154:155], s[8:9], v[32:33] op_sel_hi:[1,0,1]
	v_pk_fma_f32 v[30:31], v[152:153], s[8:9], v[30:31] op_sel_hi:[1,0,1]
	v_readlane_b32 s8, v106, 56
	s_nop 1
	v_pk_fma_f32 v[36:37], v[154:155], s[8:9], v[36:37] op_sel_hi:[1,0,1]
	v_pk_fma_f32 v[34:35], v[152:153], s[8:9], v[34:35] op_sel_hi:[1,0,1]
	v_readlane_b32 s8, v107, 56
	s_nop 1
	v_pk_fma_f32 v[40:41], v[154:155], s[8:9], v[40:41] op_sel_hi:[1,0,1]
	v_pk_fma_f32 v[38:39], v[152:153], s[8:9], v[38:39] op_sel_hi:[1,0,1]
	v_readlane_b32 s8, v108, 56
	s_nop 1
	v_pk_fma_f32 v[44:45], v[154:155], s[8:9], v[44:45] op_sel_hi:[1,0,1]
	v_pk_fma_f32 v[42:43], v[152:153], s[8:9], v[42:43] op_sel_hi:[1,0,1]
	v_readlane_b32 s8, v109, 56
	s_nop 1
	v_pk_fma_f32 v[52:53], v[154:155], s[8:9], v[52:53] op_sel_hi:[1,0,1]
	v_pk_fma_f32 v[50:51], v[152:153], s[8:9], v[50:51] op_sel_hi:[1,0,1]
	v_readlane_b32 s8, v110, 56
	s_nop 1
	v_pk_fma_f32 v[56:57], v[154:155], s[8:9], v[56:57] op_sel_hi:[1,0,1]
	v_pk_fma_f32 v[54:55], v[152:153], s[8:9], v[54:55] op_sel_hi:[1,0,1]
	v_readlane_b32 s8, v111, 56
	s_nop 0
	v_pk_fma_f32 v[60:61], v[154:155], s[8:9], v[60:61] op_sel_hi:[1,0,1]
	v_pk_fma_f32 v[58:59], v[152:153], s[8:9], v[58:59] op_sel_hi:[1,0,1]
	v_readlane_b32 s8, v1, 57
	s_waitcnt vmcnt(6)
	s_nop 0
	v_pk_fma_f32 v[24:25], v[158:159], s[8:9], v[24:25] op_sel_hi:[1,0,1]
	v_pk_fma_f32 v[22:23], v[156:157], s[8:9], v[22:23] op_sel_hi:[1,0,1]
	v_readlane_b32 s8, v104, 57
	s_nop 1
	v_pk_fma_f32 v[28:29], v[158:159], s[8:9], v[28:29] op_sel_hi:[1,0,1]
	v_pk_fma_f32 v[26:27], v[156:157], s[8:9], v[26:27] op_sel_hi:[1,0,1]
	v_readlane_b32 s8, v105, 57
	s_nop 1
	v_pk_fma_f32 v[32:33], v[158:159], s[8:9], v[32:33] op_sel_hi:[1,0,1]
	v_pk_fma_f32 v[30:31], v[156:157], s[8:9], v[30:31] op_sel_hi:[1,0,1]
	v_readlane_b32 s8, v106, 57
	s_nop 1
	v_pk_fma_f32 v[36:37], v[158:159], s[8:9], v[36:37] op_sel_hi:[1,0,1]
	v_pk_fma_f32 v[34:35], v[156:157], s[8:9], v[34:35] op_sel_hi:[1,0,1]
	v_readlane_b32 s8, v107, 57
	s_nop 1
	v_pk_fma_f32 v[40:41], v[158:159], s[8:9], v[40:41] op_sel_hi:[1,0,1]
	v_pk_fma_f32 v[38:39], v[156:157], s[8:9], v[38:39] op_sel_hi:[1,0,1]
	v_readlane_b32 s8, v108, 57
	s_nop 1
	v_pk_fma_f32 v[44:45], v[158:159], s[8:9], v[44:45] op_sel_hi:[1,0,1]
	v_pk_fma_f32 v[42:43], v[156:157], s[8:9], v[42:43] op_sel_hi:[1,0,1]
	v_readlane_b32 s8, v109, 57
	s_nop 1
	v_pk_fma_f32 v[52:53], v[158:159], s[8:9], v[52:53] op_sel_hi:[1,0,1]
	v_pk_fma_f32 v[50:51], v[156:157], s[8:9], v[50:51] op_sel_hi:[1,0,1]
	v_readlane_b32 s8, v110, 57
	s_nop 1
	v_pk_fma_f32 v[56:57], v[158:159], s[8:9], v[56:57] op_sel_hi:[1,0,1]
	v_pk_fma_f32 v[54:55], v[156:157], s[8:9], v[54:55] op_sel_hi:[1,0,1]
	v_readlane_b32 s8, v111, 57
	s_nop 0
	v_pk_fma_f32 v[60:61], v[158:159], s[8:9], v[60:61] op_sel_hi:[1,0,1]
	v_pk_fma_f32 v[58:59], v[156:157], s[8:9], v[58:59] op_sel_hi:[1,0,1]
	v_readlane_b32 s8, v1, 58
	s_waitcnt vmcnt(5)
	s_nop 0
	v_pk_fma_f32 v[24:25], v[162:163], s[8:9], v[24:25] op_sel_hi:[1,0,1]
	v_pk_fma_f32 v[22:23], v[160:161], s[8:9], v[22:23] op_sel_hi:[1,0,1]
	v_readlane_b32 s8, v104, 58
	s_nop 1
	v_pk_fma_f32 v[28:29], v[162:163], s[8:9], v[28:29] op_sel_hi:[1,0,1]
	v_pk_fma_f32 v[26:27], v[160:161], s[8:9], v[26:27] op_sel_hi:[1,0,1]
	v_readlane_b32 s8, v105, 58
	s_nop 1
	v_pk_fma_f32 v[32:33], v[162:163], s[8:9], v[32:33] op_sel_hi:[1,0,1]
	v_pk_fma_f32 v[30:31], v[160:161], s[8:9], v[30:31] op_sel_hi:[1,0,1]
	v_readlane_b32 s8, v106, 58
	s_nop 1
	v_pk_fma_f32 v[36:37], v[162:163], s[8:9], v[36:37] op_sel_hi:[1,0,1]
	v_pk_fma_f32 v[34:35], v[160:161], s[8:9], v[34:35] op_sel_hi:[1,0,1]
	v_readlane_b32 s8, v107, 58
	s_nop 1
	v_pk_fma_f32 v[40:41], v[162:163], s[8:9], v[40:41] op_sel_hi:[1,0,1]
	v_pk_fma_f32 v[38:39], v[160:161], s[8:9], v[38:39] op_sel_hi:[1,0,1]
	v_readlane_b32 s8, v108, 58
	s_nop 1
	v_pk_fma_f32 v[44:45], v[162:163], s[8:9], v[44:45] op_sel_hi:[1,0,1]
	v_pk_fma_f32 v[42:43], v[160:161], s[8:9], v[42:43] op_sel_hi:[1,0,1]
	v_readlane_b32 s8, v109, 58
	s_nop 1
	v_pk_fma_f32 v[52:53], v[162:163], s[8:9], v[52:53] op_sel_hi:[1,0,1]
	v_pk_fma_f32 v[50:51], v[160:161], s[8:9], v[50:51] op_sel_hi:[1,0,1]
	v_readlane_b32 s8, v110, 58
	s_nop 1
	v_pk_fma_f32 v[56:57], v[162:163], s[8:9], v[56:57] op_sel_hi:[1,0,1]
	v_pk_fma_f32 v[54:55], v[160:161], s[8:9], v[54:55] op_sel_hi:[1,0,1]
	v_readlane_b32 s8, v111, 58
	s_nop 0
	v_pk_fma_f32 v[162:163], v[162:163], s[8:9], v[60:61] op_sel_hi:[1,0,1]
	v_pk_fma_f32 v[160:161], v[160:161], s[8:9], v[58:59] op_sel_hi:[1,0,1]
	v_readlane_b32 s8, v1, 59
	s_waitcnt vmcnt(4)
	s_nop 0
	v_pk_fma_f32 v[24:25], v[166:167], s[8:9], v[24:25] op_sel_hi:[1,0,1]
	v_pk_fma_f32 v[22:23], v[164:165], s[8:9], v[22:23] op_sel_hi:[1,0,1]
	v_readlane_b32 s8, v104, 59
	s_nop 1
	v_pk_fma_f32 v[28:29], v[166:167], s[8:9], v[28:29] op_sel_hi:[1,0,1]
	v_pk_fma_f32 v[26:27], v[164:165], s[8:9], v[26:27] op_sel_hi:[1,0,1]
	v_readlane_b32 s8, v105, 59
	s_nop 1
	v_pk_fma_f32 v[32:33], v[166:167], s[8:9], v[32:33] op_sel_hi:[1,0,1]
	v_pk_fma_f32 v[30:31], v[164:165], s[8:9], v[30:31] op_sel_hi:[1,0,1]
	v_readlane_b32 s8, v106, 59
	s_nop 1
	v_pk_fma_f32 v[36:37], v[166:167], s[8:9], v[36:37] op_sel_hi:[1,0,1]
	v_pk_fma_f32 v[34:35], v[164:165], s[8:9], v[34:35] op_sel_hi:[1,0,1]
	v_readlane_b32 s8, v107, 59
	s_nop 1
	v_pk_fma_f32 v[40:41], v[166:167], s[8:9], v[40:41] op_sel_hi:[1,0,1]
	v_pk_fma_f32 v[38:39], v[164:165], s[8:9], v[38:39] op_sel_hi:[1,0,1]
	v_readlane_b32 s8, v108, 59
	s_nop 1
	v_pk_fma_f32 v[44:45], v[166:167], s[8:9], v[44:45] op_sel_hi:[1,0,1]
	v_pk_fma_f32 v[42:43], v[164:165], s[8:9], v[42:43] op_sel_hi:[1,0,1]
	v_readlane_b32 s8, v109, 59
	s_nop 1
	v_pk_fma_f32 v[52:53], v[166:167], s[8:9], v[52:53] op_sel_hi:[1,0,1]
	v_pk_fma_f32 v[50:51], v[164:165], s[8:9], v[50:51] op_sel_hi:[1,0,1]
	v_readlane_b32 s8, v110, 59
	s_nop 1
	v_pk_fma_f32 v[56:57], v[166:167], s[8:9], v[56:57] op_sel_hi:[1,0,1]
	v_pk_fma_f32 v[54:55], v[164:165], s[8:9], v[54:55] op_sel_hi:[1,0,1]
	v_readlane_b32 s8, v111, 59
	s_nop 0
	v_pk_fma_f32 v[166:167], v[166:167], s[8:9], v[162:163] op_sel_hi:[1,0,1]
	v_pk_fma_f32 v[164:165], v[164:165], s[8:9], v[160:161] op_sel_hi:[1,0,1]
	v_readlane_b32 s8, v1, 60
	s_waitcnt vmcnt(3)
	s_nop 0
	v_pk_fma_f32 v[24:25], v[170:171], s[8:9], v[24:25] op_sel_hi:[1,0,1]
	v_pk_fma_f32 v[22:23], v[168:169], s[8:9], v[22:23] op_sel_hi:[1,0,1]
	v_readlane_b32 s8, v104, 60
	s_nop 1
	v_pk_fma_f32 v[28:29], v[170:171], s[8:9], v[28:29] op_sel_hi:[1,0,1]
	v_pk_fma_f32 v[26:27], v[168:169], s[8:9], v[26:27] op_sel_hi:[1,0,1]
	v_readlane_b32 s8, v105, 60
	s_nop 1
	v_pk_fma_f32 v[32:33], v[170:171], s[8:9], v[32:33] op_sel_hi:[1,0,1]
	v_pk_fma_f32 v[30:31], v[168:169], s[8:9], v[30:31] op_sel_hi:[1,0,1]
	v_readlane_b32 s8, v106, 60
	s_nop 1
	v_pk_fma_f32 v[36:37], v[170:171], s[8:9], v[36:37] op_sel_hi:[1,0,1]
	v_pk_fma_f32 v[34:35], v[168:169], s[8:9], v[34:35] op_sel_hi:[1,0,1]
	v_readlane_b32 s8, v107, 60
	s_nop 1
	v_pk_fma_f32 v[40:41], v[170:171], s[8:9], v[40:41] op_sel_hi:[1,0,1]
	v_pk_fma_f32 v[38:39], v[168:169], s[8:9], v[38:39] op_sel_hi:[1,0,1]
	v_readlane_b32 s8, v108, 60
	s_nop 1
	v_pk_fma_f32 v[44:45], v[170:171], s[8:9], v[44:45] op_sel_hi:[1,0,1]
	v_pk_fma_f32 v[42:43], v[168:169], s[8:9], v[42:43] op_sel_hi:[1,0,1]
	v_readlane_b32 s8, v109, 60
	s_nop 1
	v_pk_fma_f32 v[160:161], v[170:171], s[8:9], v[52:53] op_sel_hi:[1,0,1]
	v_pk_fma_f32 v[162:163], v[168:169], s[8:9], v[50:51] op_sel_hi:[1,0,1]
	v_readlane_b32 s8, v110, 60
	s_nop 1
	v_pk_fma_f32 v[50:51], v[170:171], s[8:9], v[56:57] op_sel_hi:[1,0,1]
	v_pk_fma_f32 v[52:53], v[168:169], s[8:9], v[54:55] op_sel_hi:[1,0,1]
	v_readlane_b32 s8, v111, 60
	s_nop 0
	v_pk_fma_f32 v[170:171], v[170:171], s[8:9], v[166:167] op_sel_hi:[1,0,1]
	v_pk_fma_f32 v[168:169], v[168:169], s[8:9], v[164:165] op_sel_hi:[1,0,1]
	v_readlane_b32 s8, v1, 61
	s_waitcnt vmcnt(2)
	s_nop 0
	v_pk_fma_f32 v[164:165], v[174:175], s[8:9], v[24:25] op_sel_hi:[1,0,1]
	v_pk_fma_f32 v[166:167], v[172:173], s[8:9], v[22:23] op_sel_hi:[1,0,1]
	v_readlane_b32 s8, v104, 61
	s_nop 1
	v_pk_fma_f32 v[22:23], v[174:175], s[8:9], v[28:29] op_sel_hi:[1,0,1]
	v_pk_fma_f32 v[24:25], v[172:173], s[8:9], v[26:27] op_sel_hi:[1,0,1]
	v_readlane_b32 s8, v105, 61
	s_nop 1
	v_pk_fma_f32 v[26:27], v[174:175], s[8:9], v[32:33] op_sel_hi:[1,0,1]
	v_pk_fma_f32 v[28:29], v[172:173], s[8:9], v[30:31] op_sel_hi:[1,0,1]
	v_readlane_b32 s8, v106, 61
	s_nop 1
	v_pk_fma_f32 v[30:31], v[174:175], s[8:9], v[36:37] op_sel_hi:[1,0,1]
	v_pk_fma_f32 v[32:33], v[172:173], s[8:9], v[34:35] op_sel_hi:[1,0,1]
	v_readlane_b32 s8, v107, 61
	s_nop 1
	v_pk_fma_f32 v[34:35], v[174:175], s[8:9], v[40:41] op_sel_hi:[1,0,1]
	v_pk_fma_f32 v[36:37], v[172:173], s[8:9], v[38:39] op_sel_hi:[1,0,1]
	v_readlane_b32 s8, v108, 61
	s_nop 1
	v_pk_fma_f32 v[38:39], v[174:175], s[8:9], v[44:45] op_sel_hi:[1,0,1]
	v_pk_fma_f32 v[40:41], v[172:173], s[8:9], v[42:43] op_sel_hi:[1,0,1]
	v_readlane_b32 s8, v109, 61
	s_nop 1
	v_pk_fma_f32 v[42:43], v[174:175], s[8:9], v[160:161] op_sel_hi:[1,0,1]
	v_pk_fma_f32 v[44:45], v[172:173], s[8:9], v[162:163] op_sel_hi:[1,0,1]
	v_readlane_b32 s8, v110, 61
	s_nop 1
	v_pk_fma_f32 v[160:161], v[174:175], s[8:9], v[50:51] op_sel_hi:[1,0,1]
	v_pk_fma_f32 v[162:163], v[172:173], s[8:9], v[52:53] op_sel_hi:[1,0,1]
	v_readlane_b32 s8, v111, 61
	s_nop 0
	v_pk_fma_f32 v[174:175], v[174:175], s[8:9], v[170:171] op_sel_hi:[1,0,1]
	v_pk_fma_f32 v[172:173], v[172:173], s[8:9], v[168:169] op_sel_hi:[1,0,1]
	v_readlane_b32 s8, v1, 62
	s_waitcnt vmcnt(1)
	s_nop 0
	v_pk_fma_f32 v[168:169], v[178:179], s[8:9], v[164:165] op_sel_hi:[1,0,1]
	v_pk_fma_f32 v[170:171], v[176:177], s[8:9], v[166:167] op_sel_hi:[1,0,1]
	v_readlane_b32 s8, v104, 62
	s_nop 1
	v_pk_fma_f32 v[164:165], v[178:179], s[8:9], v[22:23] op_sel_hi:[1,0,1]
	v_pk_fma_f32 v[166:167], v[176:177], s[8:9], v[24:25] op_sel_hi:[1,0,1]
	v_readlane_b32 s8, v105, 62
	s_nop 1
	v_pk_fma_f32 v[50:51], v[178:179], s[8:9], v[26:27] op_sel_hi:[1,0,1]
	v_pk_fma_f32 v[52:53], v[176:177], s[8:9], v[28:29] op_sel_hi:[1,0,1]
	v_readlane_b32 s8, v106, 62
	s_nop 1
	v_pk_fma_f32 v[54:55], v[178:179], s[8:9], v[30:31] op_sel_hi:[1,0,1]
	v_pk_fma_f32 v[56:57], v[176:177], s[8:9], v[32:33] op_sel_hi:[1,0,1]
	v_readlane_b32 s8, v107, 62
	s_nop 1
	v_pk_fma_f32 v[58:59], v[178:179], s[8:9], v[34:35] op_sel_hi:[1,0,1]
	v_pk_fma_f32 v[60:61], v[176:177], s[8:9], v[36:37] op_sel_hi:[1,0,1]
	v_readlane_b32 s8, v108, 62
	s_nop 1
	v_pk_fma_f32 v[156:157], v[178:179], s[8:9], v[38:39] op_sel_hi:[1,0,1]
	v_pk_fma_f32 v[158:159], v[176:177], s[8:9], v[40:41] op_sel_hi:[1,0,1]
	v_readlane_b32 s8, v109, 62
	s_nop 1
	v_pk_fma_f32 v[152:153], v[178:179], s[8:9], v[42:43] op_sel_hi:[1,0,1]
	v_pk_fma_f32 v[154:155], v[176:177], s[8:9], v[44:45] op_sel_hi:[1,0,1]
	v_readlane_b32 s8, v110, 62
	s_nop 1
	v_pk_fma_f32 v[160:161], v[178:179], s[8:9], v[160:161] op_sel_hi:[1,0,1]
	v_pk_fma_f32 v[162:163], v[176:177], s[8:9], v[162:163] op_sel_hi:[1,0,1]
	v_readlane_b32 s8, v111, 62
	s_nop 0
	v_pk_fma_f32 v[178:179], v[178:179], s[8:9], v[174:175] op_sel_hi:[1,0,1]
	v_pk_fma_f32 v[176:177], v[176:177], s[8:9], v[172:173] op_sel_hi:[1,0,1]
	v_readlane_b32 s8, v1, 63
	s_waitcnt vmcnt(0)
	s_nop 0
	v_pk_fma_f32 v[24:25], v[182:183], s[8:9], v[168:169] op_sel_hi:[1,0,1]
	v_pk_fma_f32 v[22:23], v[180:181], s[8:9], v[170:171] op_sel_hi:[1,0,1]
	v_readlane_b32 s8, v104, 63
	s_nop 1
	v_pk_fma_f32 v[28:29], v[182:183], s[8:9], v[164:165] op_sel_hi:[1,0,1]
	v_pk_fma_f32 v[26:27], v[180:181], s[8:9], v[166:167] op_sel_hi:[1,0,1]
	v_readlane_b32 s8, v105, 63
	s_nop 1
	v_pk_fma_f32 v[32:33], v[182:183], s[8:9], v[50:51] op_sel_hi:[1,0,1]
	v_pk_fma_f32 v[30:31], v[180:181], s[8:9], v[52:53] op_sel_hi:[1,0,1]
	v_readlane_b32 s8, v106, 63
	s_nop 1
	v_pk_fma_f32 v[36:37], v[182:183], s[8:9], v[54:55] op_sel_hi:[1,0,1]
	v_pk_fma_f32 v[34:35], v[180:181], s[8:9], v[56:57] op_sel_hi:[1,0,1]
	v_readlane_b32 s8, v107, 63
	s_nop 1
	v_pk_fma_f32 v[40:41], v[182:183], s[8:9], v[58:59] op_sel_hi:[1,0,1]
	v_pk_fma_f32 v[38:39], v[180:181], s[8:9], v[60:61] op_sel_hi:[1,0,1]
	v_readlane_b32 s8, v108, 63
	s_nop 1
	v_pk_fma_f32 v[44:45], v[182:183], s[8:9], v[156:157] op_sel_hi:[1,0,1]
	v_pk_fma_f32 v[42:43], v[180:181], s[8:9], v[158:159] op_sel_hi:[1,0,1]
	v_readlane_b32 s8, v109, 63
	s_nop 1
	v_pk_fma_f32 v[52:53], v[182:183], s[8:9], v[152:153] op_sel_hi:[1,0,1]
	v_pk_fma_f32 v[50:51], v[180:181], s[8:9], v[154:155] op_sel_hi:[1,0,1]
	v_readlane_b32 s8, v110, 63
	s_nop 1
	v_pk_fma_f32 v[56:57], v[182:183], s[8:9], v[160:161] op_sel_hi:[1,0,1]
	v_pk_fma_f32 v[54:55], v[180:181], s[8:9], v[162:163] op_sel_hi:[1,0,1]
	v_readlane_b32 s8, v111, 63
	v_pk_fma_f32 v[60:61], v[182:183], s[8:9], v[178:179] op_sel_hi:[1,0,1]
	v_pk_fma_f32 v[58:59], v[180:181], s[8:9], v[176:177] op_sel_hi:[1,0,1]
	s_add_i32 s5, s5, 1
	s_mov_b64 s[6:7], 0x900000
	s_cmp_eq_u32 s5, 8
	v_lshl_add_u64 v[98:99], v[98:99], 0, s[6:7]
	s_cbranch_scc0 .LBB0_15
	s_and_saveexec_b64 s[6:7], s[0:1]
	s_cbranch_execz .LBB0_20
	ds_write_b128 v103, v[22:25]
	ds_write_b128 v103, v[26:29] offset:576
	ds_write_b128 v103, v[30:33] offset:1152
	ds_write_b128 v103, v[34:37] offset:1728
	ds_write_b128 v103, v[38:41] offset:2304
	ds_write_b128 v103, v[42:45] offset:2880
	ds_write_b128 v103, v[50:53] offset:3456
	ds_write_b128 v103, v[54:57] offset:4032
	ds_write_b128 v103, v[58:61] offset:4608
